# pipelined EpiRes/EpiMla epilogue loads, MLA flash K/V LDS double-buffered with one barrier per tile
# speedup vs baseline: 1.0716x; 1.0360x over previous
; template <int K> __device__ __forceinline__ float swz(float v) { return __int_as_float(__builtin_amdgcn_ds_swizzle(__float_as_int(v), (K << 10) | 0x1f)); }
; __device__ __forceinline__ float x32_sum(float v) { auto r = __builtin_amdgcn_permlane32_swap(__float_as_uint(v), __float_as_uint(v), false, false); return __uint_as_float(r[0]) + __uint_as_float(r[1]); }
;     __device__ __forceinline__ void operator()(const f32x4 (&acc)[2][2][4][2], const Unit& u, int wr, int wc, int, int) const {
;     ...
;         const int rowb = u.pm * BM + wr * 64 + fr;
; #pragma unroll
;         for (int ai = 0; ai < 2; ++ai)
; #pragma unroll
;             for (int m = 0; m < 4; ++m) {
;                 const int row = rowb + ai * HALF + m * 16;
;                 float ss = 0.f;
; #pragma unroll
;                 for (int j = 0; j < 4; ++j) ss += acc[ai][0][m][0][j] * acc[ai][0][m][0][j] + acc[ai][0][m][1][j] * acc[ai][0][m][1][j] + acc[ai][1][m][0][j] * acc[ai][1][m][0][j] + acc[ai][1][m][1][j] * acc[ai][1][m][1][j];
;                 ss += ::swz<16>(ss); ss = ::x32_sum(ss);
;                 float rs = rsqrtf(ss * inv_cnt + 1e-6f) * sc; rs = is_v ? 1.0f : rs;
;                 const int pos = row & 2047, pp = rot ? ((fq & 1) ? (pos & 63) : (pos >> 6)) : 0;
;                 const float* rt = rope + pp * 16;
;                 bf16_t* dst = obase + (unsigned)(row * ostride + ocol);
; #pragma unroll
;                 for (int n = 0; n < 2; ++n) {
;                     const f32x4 g1 = *(const f32x4*)(g + 4 * n), g2 = *(const f32x4*)(g + sbj + 4 * n);
;                     const f32x4 t0 = *(const f32x4*)(rt + 8 * n), t1 = *(const f32x4*)(rt + 8 * n + 4);
;                     const f32x4 c = (f32x4){t0[0], t0[2], t1[0], t1[2]}, s = (f32x4){t0[1], t0[3], t1[1], t1[3]};
;                     const f32x4 a1 = acc[ai][0][m][n] * rs * g1, a2 = acc[ai][1][m][n] * rs * g2;
;                     const f32x4 o1 = a1 * c - a2 * s, o2 = a1 * s + a2 * c;
;                     if (st_ok) { u32x2 w; w.x = cvt_pk_bf16(o1[0], o1[1]); w.y = cvt_pk_bf16(o1[2], o1[3]); *(u32x2*)(dst + 4 * n) = w;
;                         w.x = cvt_pk_bf16(o2[0], o2[1]); w.y = cvt_pk_bf16(o2[2], o2[3]); *(u32x2*)(dst + sbj + 4 * n) = w; }
;                 }
.LBB0_669:
	v_and_b32_e32 v161, 15, v140
	v_mov_b32_e32 v140, 0x3c800000
	v_mov_b32_e32 v143, 0x3d000000
	v_lshlrev_b32_e32 v138, 2, v138
	v_mov_b32_e32 v139, v0
	v_cndmask_b32_e64 v159, v140, v143, s[42:43]
	v_mov_b32_e32 v140, 0x3e16c740
	v_lshl_add_u64 v[138:139], s[2:3], 0, v[138:139]
	global_load_dwordx4 v[172:175], v[138:139], off
	s_and_b64 s[2:3], s[40:41], exec
	v_cndmask_b32_e64 v143, 1.0, v140, s[40:41]
	v_cmp_gt_u32_e64 s[40:41], 2, v141
	v_mul_f32_e32 v140, v118, v118
	v_mul_f32_e32 v141, v119, v119
	v_fmac_f32_e32 v140, v126, v126
	v_fmac_f32_e32 v141, v127, v127
	v_fmac_f32_e32 v140, v122, v122
	v_fmac_f32_e32 v141, v123, v123
	v_fmac_f32_e32 v140, v114, v114
	v_fmac_f32_e32 v141, v115, v115
	v_add_f32_e32 v140, v140, v141
	v_mul_f32_e32 v141, v120, v120
	v_fmac_f32_e32 v141, v128, v128
	s_cselect_b32 s3, 0x16b98000, s76
	v_fmac_f32_e32 v141, v124, v124
	s_cselect_b32 s2, 0, 0
	s_add_u32 s60, s56, s3
	v_fmac_f32_e32 v141, v116, v116
	s_addc_u32 s61, s57, s2
	v_add_f32_e32 v140, v141, v140
	v_mul_f32_e32 v141, v121, v121
	s_cmpk_lt_i32 s54, 0x80
	v_fmac_f32_e32 v141, v129, v129
	s_cselect_b64 s[2:3], -1, 0
	v_fmac_f32_e32 v141, v125, v125
	s_and_b64 vcc, s[42:43], s[2:3]
	s_xor_b64 s[2:3], s[42:43], -1
	v_fmac_f32_e32 v141, v117, v117
	s_or_b64 s[20:21], s[2:3], s[40:41]
	v_cmp_eq_u32_e64 s[40:41], 0, v144
	v_add_f32_e32 v144, v141, v140
	ds_swizzle_b32 v145, v144 offset:swizzle(SWAP,16)
	s_lshl_b32 s2, s54, 8
	s_add_i32 s5, s2, s78
	s_and_b64 s[2:3], s[42:43], exec
	s_cselect_b32 s16, 8, 32
	s_waitcnt lgkmcnt(0)
	v_add_f32_e32 v158, v144, v145
	s_lshl_b32 s54, s16, 2
	v_mov_b32_e32 v162, v158
	v_or_b32_e32 v160, s5, v161
	v_lshl_add_u64 v[140:141], v[138:139], 0, s[54:55]
	s_bfe_u32 s17, s5, 0x50006
	v_permlane32_swap_b32_e32 v158, v162
	s_and_saveexec_b64 s[2:3], s[20:21]
	v_add_f32_e32 v146, v158, v162
	v_mad_u64_u32 v[144:145], s[42:43], s26, v160, v[142:143]
	v_fmaak_f32 v146, v159, v146, 0x358637bd
	v_cmp_gt_f32_e64 s[42:43], s88, v146
	v_mul_f32_e32 v147, 0x4b800000, v146
	v_mov_b32_e32 v145, v0
	v_cndmask_b32_e64 v146, v146, v147, s[42:43]
	v_rsq_f32_e32 v146, v146
	v_lshl_add_u64 v[156:157], v[144:145], 1, s[60:61]
	s_lshl_b32 s54, s16, 1
	v_lshl_add_u64 v[144:145], v[156:157], 0, s[54:55]
	v_mul_f32_e32 v147, 0x45800000, v146
	v_cndmask_b32_e64 v146, v146, v147, s[42:43]
	v_mul_f32_e32 v146, v143, v146
	v_cndmask_b32_e64 v158, v146, 1.0, s[50:51]
	v_mov_b32_e32 v146, s17
	v_cndmask_b32_e64 v146, v161, v146, s[40:41]
	v_lshlrev_b32_e32 v146, 4, v146
	v_cndmask_b32_e32 v146, 0, v146, vcc
	v_lshlrev_b32_e32 v170, 2, v146
	global_load_dwordx4 v[176:179], v170, s[22:23]
	global_load_dwordx4 v[180:183], v170, s[22:23] offset:16
	global_load_dwordx4 v[184:187], v[140:141], off
	global_load_dwordx4 v[188:191], v[138:139], off offset:16
	global_load_dwordx4 v[192:195], v170, s[22:23] offset:32
	global_load_dwordx4 v[196:199], v170, s[22:23] offset:48
	global_load_dwordx4 v[200:203], v[140:141], off offset:16
	v_pk_mul_f32 v[146:147], v[128:129], v[158:159] op_sel_hi:[1,0]
	v_pk_mul_f32 v[148:149], v[126:127], v[158:159] op_sel_hi:[1,0]
	global_load_dwordx4 v[204:207], v[138:139], off
	v_pk_mul_f32 v[150:151], v[122:123], v[158:159] op_sel_hi:[1,0]
	v_pk_mul_f32 v[152:153], v[124:125], v[158:159] op_sel_hi:[1,0]
	s_waitcnt vmcnt(8)
	v_pk_mul_f32 v[148:149], v[148:149], v[172:173]
	v_pk_mul_f32 v[146:147], v[146:147], v[174:175]
	s_waitcnt vmcnt(6)
	v_mov_b32_e32 v166, v180
	s_waitcnt vmcnt(5)
	v_pk_mul_f32 v[124:125], v[152:153], v[186:187]
	v_pk_mul_f32 v[122:123], v[150:151], v[184:185]
	v_mov_b32_e32 v150, v176
	v_mov_b32_e32 v151, v178
	v_mov_b32_e32 v167, v182
	v_mov_b32_e32 v182, v181
	v_mov_b32_e32 v178, v177
	v_pk_mul_f32 v[152:153], v[150:151], v[122:123]
	v_pk_mul_f32 v[168:169], v[166:167], v[124:125]
	v_pk_mul_f32 v[122:123], v[178:179], v[122:123]
	v_pk_mul_f32 v[124:125], v[182:183], v[124:125]
	v_pk_fma_f32 v[122:123], v[148:149], v[150:151], v[122:123] neg_lo:[0,0,1] neg_hi:[0,0,1]
	v_pk_fma_f32 v[124:125], v[146:147], v[166:167], v[124:125] neg_lo:[0,0,1] neg_hi:[0,0,1]
	v_pk_fma_f32 v[162:163], v[146:147], v[182:183], v[168:169]
	v_pk_fma_f32 v[126:127], v[148:149], v[178:179], v[152:153]
	v_cvt_pk_bf16_f32 v122, v122, v123
	v_cvt_pk_bf16_f32 v123, v124, v125
	global_store_dwordx2 v[156:157], v[122:123], off
	v_cvt_pk_bf16_f32 v122, v126, v127
	v_cvt_pk_bf16_f32 v123, v162, v163
	global_store_dwordx2 v[144:145], v[122:123], off
	v_pk_mul_f32 v[122:123], v[120:121], v[158:159] op_sel_hi:[1,0]
	v_pk_mul_f32 v[124:125], v[118:119], v[158:159] op_sel_hi:[1,0]
	v_pk_mul_f32 v[146:147], v[114:115], v[158:159] op_sel_hi:[1,0]
	v_pk_mul_f32 v[148:149], v[116:117], v[158:159] op_sel_hi:[1,0]
	s_waitcnt vmcnt(6)
	v_pk_mul_f32 v[126:127], v[124:125], v[188:189]
	v_pk_mul_f32 v[128:129], v[122:123], v[190:191]
	s_waitcnt vmcnt(4)
	v_mov_b32_e32 v150, v196
	s_waitcnt vmcnt(3)
	v_pk_mul_f32 v[116:117], v[148:149], v[202:203]
	v_pk_mul_f32 v[114:115], v[146:147], v[200:201]
	v_mov_b32_e32 v146, v192
	v_mov_b32_e32 v147, v194
	v_mov_b32_e32 v151, v198
	v_mov_b32_e32 v198, v197
	v_mov_b32_e32 v194, v193
	v_pk_mul_f32 v[148:149], v[146:147], v[114:115]
	v_pk_mul_f32 v[152:153], v[150:151], v[116:117]
	v_pk_mul_f32 v[114:115], v[194:195], v[114:115]
	v_pk_mul_f32 v[116:117], v[198:199], v[116:117]
	v_pk_fma_f32 v[114:115], v[126:127], v[146:147], v[114:115] neg_lo:[0,0,1] neg_hi:[0,0,1]
	v_pk_fma_f32 v[116:117], v[128:129], v[150:151], v[116:117] neg_lo:[0,0,1] neg_hi:[0,0,1]
	v_pk_fma_f32 v[122:123], v[128:129], v[198:199], v[152:153]
	v_pk_fma_f32 v[118:119], v[126:127], v[194:195], v[148:149]
	v_cvt_pk_bf16_f32 v114, v114, v115
	v_cvt_pk_bf16_f32 v115, v116, v117
	global_store_dwordx2 v[156:157], v[114:115], off offset:8
	v_cvt_pk_bf16_f32 v114, v118, v119
	v_cvt_pk_bf16_f32 v115, v122, v123
	global_store_dwordx2 v[144:145], v[114:115], off offset:8
; template <int K> __device__ __forceinline__ float swz(float v) { return __int_as_float(__builtin_amdgcn_ds_swizzle(__float_as_int(v), (K << 10) | 0x1f)); }
; __device__ __forceinline__ float x32_sum(float v) { auto r = __builtin_amdgcn_permlane32_swap(__float_as_uint(v), __float_as_uint(v), false, false); return __uint_as_float(r[0]) + __uint_as_float(r[1]); }
; __device__ __forceinline__ unsigned cvt_pk_bf16(float lo, float hi) { const f32x2c f = {lo, hi}; return __builtin_bit_cast(unsigned, __builtin_convertvector(f, bf16x2c)); }
;     __device__ __forceinline__ void operator()(const f32x4 (&acc)[2][2][4][2], const Unit& u, int wr, int wc, int, int) const {
;     ...
;                 const int row = rowb + ai * HALF + m * 16;
;                 float ss = 0.f;
; #pragma unroll
;                 for (int j = 0; j < 4; ++j) ss += acc[ai][0][m][0][j] * acc[ai][0][m][0][j] + acc[ai][0][m][1][j] * acc[ai][0][m][1][j] + acc[ai][1][m][0][j] * acc[ai][1][m][0][j] + acc[ai][1][m][1][j] * acc[ai][1][m][1][j];
;                 ss += ::swz<16>(ss); ss = ::x32_sum(ss);
;                 float rs = rsqrtf(ss * inv_cnt + 1e-6f) * sc; rs = is_v ? 1.0f : rs;
;                 const int pos = row & 2047, pp = rot ? ((fq & 1) ? (pos & 63) : (pos >> 6)) : 0;
;                 const float* rt = rope + pp * 16;
;                 bf16_t* dst = obase + (unsigned)(row * ostride + ocol);
; #pragma unroll
;                 for (int n = 0; n < 2; ++n) {
;                     const f32x4 g1 = *(const f32x4*)(g + 4 * n), g2 = *(const f32x4*)(g + sbj + 4 * n);
;                     const f32x4 t0 = *(const f32x4*)(rt + 8 * n), t1 = *(const f32x4*)(rt + 8 * n + 4);
;                     const f32x4 c = (f32x4){t0[0], t0[2], t1[0], t1[2]}, s = (f32x4){t0[1], t0[3], t1[1], t1[3]};
;                     const f32x4 a1 = acc[ai][0][m][n] * rs * g1, a2 = acc[ai][1][m][n] * rs * g2;
;                     const f32x4 o1 = a1 * c - a2 * s, o2 = a1 * s + a2 * c;
;                     if (st_ok) { u32x2 w; w.x = cvt_pk_bf16(o1[0], o1[1]); w.y = cvt_pk_bf16(o1[2], o1[3]); *(u32x2*)(dst + 4 * n) = w;
;                         w.x = cvt_pk_bf16(o2[0], o2[1]); w.y = cvt_pk_bf16(o2[2], o2[3]); *(u32x2*)(dst + sbj + 4 * n) = w; }
;                 }
.LBB0_671:
	s_or_b64 exec, exec, s[2:3]
	v_mul_f32_e32 v114, v102, v102
	v_mul_f32_e32 v115, v103, v103
	v_fmac_f32_e32 v114, v110, v110
	v_fmac_f32_e32 v115, v111, v111
	v_fmac_f32_e32 v114, v106, v106
	v_fmac_f32_e32 v115, v107, v107
	v_fmac_f32_e32 v114, v98, v98
	v_fmac_f32_e32 v115, v99, v99
	v_add_f32_e32 v114, v114, v115
	v_mul_f32_e32 v115, v104, v104
	v_fmac_f32_e32 v115, v112, v112
	v_fmac_f32_e32 v115, v108, v108
	v_fmac_f32_e32 v115, v100, v100
	v_add_f32_e32 v114, v115, v114
	v_mul_f32_e32 v115, v105, v105
	v_fmac_f32_e32 v115, v113, v113
	v_fmac_f32_e32 v115, v109, v109
	v_fmac_f32_e32 v115, v101, v101
	v_add_f32_e32 v114, v115, v114
	ds_swizzle_b32 v115, v114 offset:swizzle(SWAP,16)
	v_or_b32_e32 v119, 16, v161
	s_waitcnt lgkmcnt(0)
	v_add_f32_e32 v118, v114, v115
	v_mov_b32_e32 v120, v118
	s_nop 1
	v_permlane32_swap_b32_e32 v118, v120
	s_and_saveexec_b64 s[2:3], s[20:21]
	v_or_b32_e32 v114, 16, v160
	v_add_f32_e32 v118, v118, v120
	v_mad_u64_u32 v[114:115], s[42:43], s26, v114, v[142:143]
	v_fmaak_f32 v118, v159, v118, 0x358637bd
	v_cmp_gt_f32_e64 s[42:43], s88, v118
	v_mul_f32_e32 v120, 0x4b800000, v118
	v_mov_b32_e32 v115, v0
	v_cndmask_b32_e64 v118, v118, v120, s[42:43]
	v_rsq_f32_e32 v118, v118
	v_lshl_add_u64 v[116:117], v[114:115], 1, s[60:61]
	s_lshl_b32 s54, s16, 1
	v_lshl_add_u64 v[114:115], v[116:117], 0, s[54:55]
	v_mul_f32_e32 v120, 0x45800000, v118
	v_cndmask_b32_e64 v118, v118, v120, s[42:43]
	v_mov_b32_e32 v120, s17
	v_cndmask_b32_e64 v120, v119, v120, s[40:41]
	v_mul_f32_e32 v118, v143, v118
	v_lshlrev_b32_e32 v120, 4, v120
	v_cndmask_b32_e64 v118, v118, 1.0, s[50:51]
	v_cndmask_b32_e32 v120, 0, v120, vcc
	v_lshlrev_b32_e32 v150, 2, v120
	global_load_dwordx4 v[172:175], v150, s[22:23]
	global_load_dwordx4 v[176:179], v150, s[22:23] offset:16
	global_load_dwordx4 v[180:183], v[140:141], off
	global_load_dwordx4 v[184:187], v[138:139], off offset:16
	global_load_dwordx4 v[188:191], v150, s[22:23] offset:32
	global_load_dwordx4 v[192:195], v150, s[22:23] offset:48
	global_load_dwordx4 v[196:199], v[140:141], off offset:16
	v_pk_mul_f32 v[120:121], v[112:113], v[118:119] op_sel_hi:[1,0]
	v_pk_mul_f32 v[122:123], v[110:111], v[118:119] op_sel_hi:[1,0]
	global_load_dwordx4 v[200:203], v[138:139], off
	v_pk_mul_f32 v[128:129], v[106:107], v[118:119] op_sel_hi:[1,0]
	v_pk_mul_f32 v[144:145], v[108:109], v[118:119] op_sel_hi:[1,0]
	s_waitcnt vmcnt(12)
	v_pk_mul_f32 v[124:125], v[122:123], v[204:205]
	v_pk_mul_f32 v[126:127], v[120:121], v[206:207]
	s_waitcnt vmcnt(6)
	v_mov_b32_e32 v146, v176
	s_waitcnt vmcnt(5)
	v_pk_mul_f32 v[108:109], v[144:145], v[182:183]
	v_pk_mul_f32 v[106:107], v[128:129], v[180:181]
	v_mov_b32_e32 v128, v172
	v_mov_b32_e32 v129, v174
	v_mov_b32_e32 v147, v178
	v_mov_b32_e32 v178, v177
	v_mov_b32_e32 v174, v173
	v_pk_mul_f32 v[144:145], v[128:129], v[106:107]
	v_pk_mul_f32 v[148:149], v[146:147], v[108:109]
	v_pk_mul_f32 v[106:107], v[174:175], v[106:107]
	v_pk_mul_f32 v[108:109], v[178:179], v[108:109]
	v_pk_fma_f32 v[106:107], v[124:125], v[128:129], v[106:107] neg_lo:[0,0,1] neg_hi:[0,0,1]
	v_pk_fma_f32 v[108:109], v[126:127], v[146:147], v[108:109] neg_lo:[0,0,1] neg_hi:[0,0,1]
	v_pk_fma_f32 v[120:121], v[126:127], v[178:179], v[148:149]
	v_pk_fma_f32 v[110:111], v[124:125], v[174:175], v[144:145]
	v_cvt_pk_bf16_f32 v106, v106, v107
	v_cvt_pk_bf16_f32 v107, v108, v109
	global_store_dwordx2 v[116:117], v[106:107], off
	v_cvt_pk_bf16_f32 v106, v110, v111
	v_cvt_pk_bf16_f32 v107, v120, v121
	global_store_dwordx2 v[114:115], v[106:107], off
	v_pk_mul_f32 v[106:107], v[104:105], v[118:119] op_sel_hi:[1,0]
	v_pk_mul_f32 v[108:109], v[102:103], v[118:119] op_sel_hi:[1,0]
	v_pk_mul_f32 v[120:121], v[98:99], v[118:119] op_sel_hi:[1,0]
	v_pk_mul_f32 v[122:123], v[100:101], v[118:119] op_sel_hi:[1,0]
	s_waitcnt vmcnt(6)
	v_pk_mul_f32 v[110:111], v[108:109], v[184:185]
	v_pk_mul_f32 v[112:113], v[106:107], v[186:187]
	s_waitcnt vmcnt(4)
	v_mov_b32_e32 v124, v192
	s_waitcnt vmcnt(3)
	v_pk_mul_f32 v[100:101], v[122:123], v[198:199]
	v_pk_mul_f32 v[98:99], v[120:121], v[196:197]
	v_mov_b32_e32 v120, v188
	v_mov_b32_e32 v121, v190
	v_mov_b32_e32 v125, v194
	v_mov_b32_e32 v194, v193
	v_mov_b32_e32 v190, v189
	v_pk_mul_f32 v[122:123], v[120:121], v[98:99]
	v_pk_mul_f32 v[126:127], v[124:125], v[100:101]
	v_pk_mul_f32 v[98:99], v[190:191], v[98:99]
	v_pk_mul_f32 v[100:101], v[194:195], v[100:101]
	v_pk_fma_f32 v[98:99], v[110:111], v[120:121], v[98:99] neg_lo:[0,0,1] neg_hi:[0,0,1]
	v_pk_fma_f32 v[100:101], v[112:113], v[124:125], v[100:101] neg_lo:[0,0,1] neg_hi:[0,0,1]
	v_pk_fma_f32 v[106:107], v[112:113], v[194:195], v[126:127]
	v_pk_fma_f32 v[102:103], v[110:111], v[190:191], v[122:123]
	v_cvt_pk_bf16_f32 v98, v98, v99
	v_cvt_pk_bf16_f32 v99, v100, v101
	global_store_dwordx2 v[116:117], v[98:99], off offset:8
	v_cvt_pk_bf16_f32 v98, v102, v103
	v_cvt_pk_bf16_f32 v99, v106, v107
	global_store_dwordx2 v[114:115], v[98:99], off offset:8
; template <int K> __device__ __forceinline__ float swz(float v) { return __int_as_float(__builtin_amdgcn_ds_swizzle(__float_as_int(v), (K << 10) | 0x1f)); }
; __device__ __forceinline__ float x32_sum(float v) { auto r = __builtin_amdgcn_permlane32_swap(__float_as_uint(v), __float_as_uint(v), false, false); return __uint_as_float(r[0]) + __uint_as_float(r[1]); }
; __device__ __forceinline__ unsigned cvt_pk_bf16(float lo, float hi) { const f32x2c f = {lo, hi}; return __builtin_bit_cast(unsigned, __builtin_convertvector(f, bf16x2c)); }
;     __device__ __forceinline__ void operator()(const f32x4 (&acc)[2][2][4][2], const Unit& u, int wr, int wc, int, int) const {
;     ...
;                 const int row = rowb + ai * HALF + m * 16;
;                 float ss = 0.f;
; #pragma unroll
;                 for (int j = 0; j < 4; ++j) ss += acc[ai][0][m][0][j] * acc[ai][0][m][0][j] + acc[ai][0][m][1][j] * acc[ai][0][m][1][j] + acc[ai][1][m][0][j] * acc[ai][1][m][0][j] + acc[ai][1][m][1][j] * acc[ai][1][m][1][j];
;                 ss += ::swz<16>(ss); ss = ::x32_sum(ss);
;                 float rs = rsqrtf(ss * inv_cnt + 1e-6f) * sc; rs = is_v ? 1.0f : rs;
;                 const int pos = row & 2047, pp = rot ? ((fq & 1) ? (pos & 63) : (pos >> 6)) : 0;
;                 const float* rt = rope + pp * 16;
;                 bf16_t* dst = obase + (unsigned)(row * ostride + ocol);
; #pragma unroll
;                 for (int n = 0; n < 2; ++n) {
;                     const f32x4 g1 = *(const f32x4*)(g + 4 * n), g2 = *(const f32x4*)(g + sbj + 4 * n);
;                     const f32x4 t0 = *(const f32x4*)(rt + 8 * n), t1 = *(const f32x4*)(rt + 8 * n + 4);
;                     const f32x4 c = (f32x4){t0[0], t0[2], t1[0], t1[2]}, s = (f32x4){t0[1], t0[3], t1[1], t1[3]};
;                     const f32x4 a1 = acc[ai][0][m][n] * rs * g1, a2 = acc[ai][1][m][n] * rs * g2;
;                     const f32x4 o1 = a1 * c - a2 * s, o2 = a1 * s + a2 * c;
;                     if (st_ok) { u32x2 w; w.x = cvt_pk_bf16(o1[0], o1[1]); w.y = cvt_pk_bf16(o1[2], o1[3]); *(u32x2*)(dst + 4 * n) = w;
;                         w.x = cvt_pk_bf16(o2[0], o2[1]); w.y = cvt_pk_bf16(o2[2], o2[3]); *(u32x2*)(dst + sbj + 4 * n) = w; }
;                 }
.LBB0_673:
	s_or_b64 exec, exec, s[2:3]
	v_mul_f32_e32 v98, v86, v86
	v_mul_f32_e32 v99, v87, v87
	v_fmac_f32_e32 v98, v94, v94
	v_fmac_f32_e32 v99, v95, v95
	v_fmac_f32_e32 v98, v90, v90
	v_fmac_f32_e32 v99, v91, v91
	v_fmac_f32_e32 v98, v82, v82
	v_fmac_f32_e32 v99, v83, v83
	v_add_f32_e32 v98, v98, v99
	v_mul_f32_e32 v99, v88, v88
	v_fmac_f32_e32 v99, v96, v96
	v_fmac_f32_e32 v99, v92, v92
	v_fmac_f32_e32 v99, v84, v84
	v_add_f32_e32 v98, v99, v98
	v_mul_f32_e32 v99, v89, v89
	v_fmac_f32_e32 v99, v97, v97
	v_fmac_f32_e32 v99, v93, v93
	v_fmac_f32_e32 v99, v85, v85
	v_add_f32_e32 v98, v99, v98
	ds_swizzle_b32 v99, v98 offset:swizzle(SWAP,16)
	v_or_b32_e32 v103, 32, v161
	s_waitcnt lgkmcnt(0)
	v_add_f32_e32 v102, v98, v99
	v_mov_b32_e32 v104, v102
	s_nop 1
	v_permlane32_swap_b32_e32 v102, v104
	s_and_saveexec_b64 s[2:3], s[20:21]
	v_or_b32_e32 v98, 32, v160
	v_add_f32_e32 v102, v102, v104
	v_mad_u64_u32 v[98:99], s[42:43], s26, v98, v[142:143]
	v_fmaak_f32 v102, v159, v102, 0x358637bd
	v_cmp_gt_f32_e64 s[42:43], s88, v102
	v_mul_f32_e32 v104, 0x4b800000, v102
	v_mov_b32_e32 v99, v0
	v_cndmask_b32_e64 v102, v102, v104, s[42:43]
	v_rsq_f32_e32 v102, v102
	v_lshl_add_u64 v[100:101], v[98:99], 1, s[60:61]
	s_lshl_b32 s54, s16, 1
	v_lshl_add_u64 v[98:99], v[100:101], 0, s[54:55]
	v_mul_f32_e32 v104, 0x45800000, v102
	v_cndmask_b32_e64 v102, v102, v104, s[42:43]
	v_mov_b32_e32 v104, s17
	v_cndmask_b32_e64 v104, v103, v104, s[40:41]
	v_mul_f32_e32 v102, v143, v102
	v_lshlrev_b32_e32 v104, 4, v104
	v_cndmask_b32_e64 v102, v102, 1.0, s[50:51]
	v_cndmask_b32_e32 v104, 0, v104, vcc
	v_lshlrev_b32_e32 v118, 2, v104
	global_load_dwordx4 v[172:175], v118, s[22:23]
	global_load_dwordx4 v[176:179], v118, s[22:23] offset:16
	global_load_dwordx4 v[180:183], v[140:141], off
	global_load_dwordx4 v[184:187], v[138:139], off offset:16
	global_load_dwordx4 v[188:191], v118, s[22:23] offset:32
	global_load_dwordx4 v[192:195], v118, s[22:23] offset:48
	global_load_dwordx4 v[196:199], v[140:141], off offset:16
	v_pk_mul_f32 v[104:105], v[96:97], v[102:103] op_sel_hi:[1,0]
	v_pk_mul_f32 v[106:107], v[94:95], v[102:103] op_sel_hi:[1,0]
	global_load_dwordx4 v[204:207], v[138:139], off
	v_pk_mul_f32 v[112:113], v[90:91], v[102:103] op_sel_hi:[1,0]
	v_pk_mul_f32 v[114:115], v[92:93], v[102:103] op_sel_hi:[1,0]
	s_waitcnt vmcnt(12)
	v_pk_mul_f32 v[108:109], v[106:107], v[200:201]
	v_pk_mul_f32 v[110:111], v[104:105], v[202:203]
	s_waitcnt vmcnt(6)
	v_mov_b32_e32 v116, v176
	s_waitcnt vmcnt(5)
	v_pk_mul_f32 v[92:93], v[114:115], v[182:183]
	v_pk_mul_f32 v[90:91], v[112:113], v[180:181]
	v_mov_b32_e32 v112, v172
	v_mov_b32_e32 v113, v174
	v_mov_b32_e32 v117, v178
	v_mov_b32_e32 v178, v177
	v_mov_b32_e32 v174, v173
	v_pk_mul_f32 v[114:115], v[112:113], v[90:91]
	v_pk_mul_f32 v[120:121], v[116:117], v[92:93]
	v_pk_mul_f32 v[90:91], v[174:175], v[90:91]
	v_pk_mul_f32 v[92:93], v[178:179], v[92:93]
	v_pk_fma_f32 v[90:91], v[108:109], v[112:113], v[90:91] neg_lo:[0,0,1] neg_hi:[0,0,1]
	v_pk_fma_f32 v[92:93], v[110:111], v[116:117], v[92:93] neg_lo:[0,0,1] neg_hi:[0,0,1]
	v_pk_fma_f32 v[104:105], v[110:111], v[178:179], v[120:121]
	v_pk_fma_f32 v[94:95], v[108:109], v[174:175], v[114:115]
	v_cvt_pk_bf16_f32 v90, v90, v91
	v_cvt_pk_bf16_f32 v91, v92, v93
	global_store_dwordx2 v[100:101], v[90:91], off
	v_cvt_pk_bf16_f32 v90, v94, v95
	v_cvt_pk_bf16_f32 v91, v104, v105
	global_store_dwordx2 v[98:99], v[90:91], off
	v_pk_mul_f32 v[90:91], v[88:89], v[102:103] op_sel_hi:[1,0]
	v_pk_mul_f32 v[92:93], v[86:87], v[102:103] op_sel_hi:[1,0]
	v_pk_mul_f32 v[104:105], v[82:83], v[102:103] op_sel_hi:[1,0]
	v_pk_mul_f32 v[106:107], v[84:85], v[102:103] op_sel_hi:[1,0]
	s_waitcnt vmcnt(6)
	v_pk_mul_f32 v[94:95], v[92:93], v[184:185]
	v_pk_mul_f32 v[96:97], v[90:91], v[186:187]
	s_waitcnt vmcnt(4)
	v_mov_b32_e32 v108, v192
	s_waitcnt vmcnt(3)
	v_pk_mul_f32 v[84:85], v[106:107], v[198:199]
	v_pk_mul_f32 v[82:83], v[104:105], v[196:197]
	v_mov_b32_e32 v104, v188
	v_mov_b32_e32 v105, v190
	v_mov_b32_e32 v109, v194
	v_mov_b32_e32 v194, v193
	v_mov_b32_e32 v190, v189
	v_pk_mul_f32 v[106:107], v[104:105], v[82:83]
	v_pk_mul_f32 v[110:111], v[108:109], v[84:85]
	v_pk_mul_f32 v[82:83], v[190:191], v[82:83]
	v_pk_mul_f32 v[84:85], v[194:195], v[84:85]
	v_pk_fma_f32 v[82:83], v[94:95], v[104:105], v[82:83] neg_lo:[0,0,1] neg_hi:[0,0,1]
	v_pk_fma_f32 v[84:85], v[96:97], v[108:109], v[84:85] neg_lo:[0,0,1] neg_hi:[0,0,1]
	v_pk_fma_f32 v[90:91], v[96:97], v[194:195], v[110:111]
	v_pk_fma_f32 v[86:87], v[94:95], v[190:191], v[106:107]
	v_cvt_pk_bf16_f32 v82, v82, v83
	v_cvt_pk_bf16_f32 v83, v84, v85
	global_store_dwordx2 v[100:101], v[82:83], off offset:8
	v_cvt_pk_bf16_f32 v82, v86, v87
	v_cvt_pk_bf16_f32 v83, v90, v91
	global_store_dwordx2 v[98:99], v[82:83], off offset:8
; template <int K> __device__ __forceinline__ float swz(float v) { return __int_as_float(__builtin_amdgcn_ds_swizzle(__float_as_int(v), (K << 10) | 0x1f)); }
; __device__ __forceinline__ float x32_sum(float v) { auto r = __builtin_amdgcn_permlane32_swap(__float_as_uint(v), __float_as_uint(v), false, false); return __uint_as_float(r[0]) + __uint_as_float(r[1]); }
; __device__ __forceinline__ unsigned cvt_pk_bf16(float lo, float hi) { const f32x2c f = {lo, hi}; return __builtin_bit_cast(unsigned, __builtin_convertvector(f, bf16x2c)); }
;     __device__ __forceinline__ void operator()(const f32x4 (&acc)[2][2][4][2], const Unit& u, int wr, int wc, int, int) const {
;     ...
;                 const int row = rowb + ai * HALF + m * 16;
;                 float ss = 0.f;
; #pragma unroll
;                 for (int j = 0; j < 4; ++j) ss += acc[ai][0][m][0][j] * acc[ai][0][m][0][j] + acc[ai][0][m][1][j] * acc[ai][0][m][1][j] + acc[ai][1][m][0][j] * acc[ai][1][m][0][j] + acc[ai][1][m][1][j] * acc[ai][1][m][1][j];
;                 ss += ::swz<16>(ss); ss = ::x32_sum(ss);
;                 float rs = rsqrtf(ss * inv_cnt + 1e-6f) * sc; rs = is_v ? 1.0f : rs;
;                 const int pos = row & 2047, pp = rot ? ((fq & 1) ? (pos & 63) : (pos >> 6)) : 0;
;                 const float* rt = rope + pp * 16;
;                 bf16_t* dst = obase + (unsigned)(row * ostride + ocol);
; #pragma unroll
;                 for (int n = 0; n < 2; ++n) {
;                     const f32x4 g1 = *(const f32x4*)(g + 4 * n), g2 = *(const f32x4*)(g + sbj + 4 * n);
;                     const f32x4 t0 = *(const f32x4*)(rt + 8 * n), t1 = *(const f32x4*)(rt + 8 * n + 4);
;                     const f32x4 c = (f32x4){t0[0], t0[2], t1[0], t1[2]}, s = (f32x4){t0[1], t0[3], t1[1], t1[3]};
;                     const f32x4 a1 = acc[ai][0][m][n] * rs * g1, a2 = acc[ai][1][m][n] * rs * g2;
;                     const f32x4 o1 = a1 * c - a2 * s, o2 = a1 * s + a2 * c;
;                     if (st_ok) { u32x2 w; w.x = cvt_pk_bf16(o1[0], o1[1]); w.y = cvt_pk_bf16(o1[2], o1[3]); *(u32x2*)(dst + 4 * n) = w;
;                         w.x = cvt_pk_bf16(o2[0], o2[1]); w.y = cvt_pk_bf16(o2[2], o2[3]); *(u32x2*)(dst + sbj + 4 * n) = w; }
;                 }
.LBB0_675:
	s_or_b64 exec, exec, s[2:3]
	v_mul_f32_e32 v82, v70, v70
	v_mul_f32_e32 v83, v71, v71
	v_fmac_f32_e32 v82, v78, v78
	v_fmac_f32_e32 v83, v79, v79
	v_fmac_f32_e32 v82, v74, v74
	v_fmac_f32_e32 v83, v75, v75
	v_fmac_f32_e32 v82, v66, v66
	v_fmac_f32_e32 v83, v67, v67
	v_add_f32_e32 v82, v82, v83
	v_mul_f32_e32 v83, v72, v72
	v_fmac_f32_e32 v83, v80, v80
	v_fmac_f32_e32 v83, v76, v76
	v_fmac_f32_e32 v83, v68, v68
	v_add_f32_e32 v82, v83, v82
	v_mul_f32_e32 v83, v73, v73
	v_fmac_f32_e32 v83, v81, v81
	v_fmac_f32_e32 v83, v77, v77
	v_fmac_f32_e32 v83, v69, v69
	v_add_f32_e32 v82, v83, v82
	ds_swizzle_b32 v83, v82 offset:swizzle(SWAP,16)
	v_or_b32_e32 v87, 48, v161
	s_waitcnt lgkmcnt(0)
	v_add_f32_e32 v86, v82, v83
	v_mov_b32_e32 v88, v86
	s_nop 1
	v_permlane32_swap_b32_e32 v86, v88
	s_and_saveexec_b64 s[2:3], s[20:21]
	v_or_b32_e32 v82, 48, v160
	v_add_f32_e32 v86, v86, v88
	v_mad_u64_u32 v[82:83], s[42:43], s26, v82, v[142:143]
	v_fmaak_f32 v86, v159, v86, 0x358637bd
	v_cmp_gt_f32_e64 s[42:43], s88, v86
	v_mul_f32_e32 v88, 0x4b800000, v86
	v_mov_b32_e32 v83, v0
	v_cndmask_b32_e64 v86, v86, v88, s[42:43]
	v_rsq_f32_e32 v86, v86
	v_lshl_add_u64 v[84:85], v[82:83], 1, s[60:61]
	s_lshl_b32 s54, s16, 1
	v_lshl_add_u64 v[82:83], v[84:85], 0, s[54:55]
	v_mul_f32_e32 v88, 0x45800000, v86
	v_cndmask_b32_e64 v86, v86, v88, s[42:43]
	v_mov_b32_e32 v88, s17
	v_cndmask_b32_e64 v88, v87, v88, s[40:41]
	v_mul_f32_e32 v86, v143, v86
	v_lshlrev_b32_e32 v88, 4, v88
	v_cndmask_b32_e64 v86, v86, 1.0, s[50:51]
	v_cndmask_b32_e32 v88, 0, v88, vcc
	v_lshlrev_b32_e32 v102, 2, v88
	global_load_dwordx4 v[172:175], v102, s[22:23]
	global_load_dwordx4 v[176:179], v102, s[22:23] offset:16
	global_load_dwordx4 v[180:183], v[140:141], off
	global_load_dwordx4 v[184:187], v[138:139], off offset:16
	global_load_dwordx4 v[188:191], v102, s[22:23] offset:32
	global_load_dwordx4 v[192:195], v102, s[22:23] offset:48
	global_load_dwordx4 v[196:199], v[140:141], off offset:16
	v_pk_mul_f32 v[88:89], v[80:81], v[86:87] op_sel_hi:[1,0]
	v_pk_mul_f32 v[90:91], v[78:79], v[86:87] op_sel_hi:[1,0]
	global_load_dwordx4 v[200:203], v[138:139], off
	v_pk_mul_f32 v[96:97], v[74:75], v[86:87] op_sel_hi:[1,0]
	v_pk_mul_f32 v[98:99], v[76:77], v[86:87] op_sel_hi:[1,0]
	s_waitcnt vmcnt(12)
	v_pk_mul_f32 v[92:93], v[90:91], v[204:205]
	v_pk_mul_f32 v[94:95], v[88:89], v[206:207]
	s_waitcnt vmcnt(6)
	v_mov_b32_e32 v100, v176
	s_waitcnt vmcnt(5)
	v_pk_mul_f32 v[76:77], v[98:99], v[182:183]
	v_pk_mul_f32 v[74:75], v[96:97], v[180:181]
	v_mov_b32_e32 v96, v172
	v_mov_b32_e32 v97, v174
	v_mov_b32_e32 v101, v178
	v_mov_b32_e32 v178, v177
	v_mov_b32_e32 v174, v173
	v_pk_mul_f32 v[98:99], v[96:97], v[74:75]
	v_pk_mul_f32 v[104:105], v[100:101], v[76:77]
	v_pk_mul_f32 v[74:75], v[174:175], v[74:75]
	v_pk_mul_f32 v[76:77], v[178:179], v[76:77]
	v_pk_fma_f32 v[74:75], v[92:93], v[96:97], v[74:75] neg_lo:[0,0,1] neg_hi:[0,0,1]
	v_pk_fma_f32 v[76:77], v[94:95], v[100:101], v[76:77] neg_lo:[0,0,1] neg_hi:[0,0,1]
	v_pk_fma_f32 v[88:89], v[94:95], v[178:179], v[104:105]
	v_pk_fma_f32 v[78:79], v[92:93], v[174:175], v[98:99]
	v_cvt_pk_bf16_f32 v74, v74, v75
	v_cvt_pk_bf16_f32 v75, v76, v77
	global_store_dwordx2 v[84:85], v[74:75], off
	v_cvt_pk_bf16_f32 v74, v78, v79
	v_cvt_pk_bf16_f32 v75, v88, v89
	global_store_dwordx2 v[82:83], v[74:75], off
	v_pk_mul_f32 v[74:75], v[72:73], v[86:87] op_sel_hi:[1,0]
	v_pk_mul_f32 v[76:77], v[70:71], v[86:87] op_sel_hi:[1,0]
	v_pk_mul_f32 v[88:89], v[66:67], v[86:87] op_sel_hi:[1,0]
	v_pk_mul_f32 v[90:91], v[68:69], v[86:87] op_sel_hi:[1,0]
	s_waitcnt vmcnt(6)
	v_pk_mul_f32 v[78:79], v[76:77], v[184:185]
	v_pk_mul_f32 v[80:81], v[74:75], v[186:187]
	s_waitcnt vmcnt(4)
	v_mov_b32_e32 v92, v192
	s_waitcnt vmcnt(3)
	v_pk_mul_f32 v[68:69], v[90:91], v[198:199]
	v_pk_mul_f32 v[66:67], v[88:89], v[196:197]
	v_mov_b32_e32 v88, v188
	v_mov_b32_e32 v89, v190
	v_mov_b32_e32 v93, v194
	v_mov_b32_e32 v194, v193
	v_mov_b32_e32 v190, v189
	v_pk_mul_f32 v[90:91], v[88:89], v[66:67]
	v_pk_mul_f32 v[94:95], v[92:93], v[68:69]
	v_pk_mul_f32 v[66:67], v[190:191], v[66:67]
	v_pk_mul_f32 v[68:69], v[194:195], v[68:69]
	v_pk_fma_f32 v[66:67], v[78:79], v[88:89], v[66:67] neg_lo:[0,0,1] neg_hi:[0,0,1]
	v_pk_fma_f32 v[68:69], v[80:81], v[92:93], v[68:69] neg_lo:[0,0,1] neg_hi:[0,0,1]
	v_pk_fma_f32 v[74:75], v[80:81], v[194:195], v[94:95]
	v_pk_fma_f32 v[70:71], v[78:79], v[190:191], v[90:91]
	v_cvt_pk_bf16_f32 v66, v66, v67
	v_cvt_pk_bf16_f32 v67, v68, v69
	global_store_dwordx2 v[84:85], v[66:67], off offset:8
	v_cvt_pk_bf16_f32 v66, v70, v71
	v_cvt_pk_bf16_f32 v67, v74, v75
	global_store_dwordx2 v[82:83], v[66:67], off offset:8
; template <int K> __device__ __forceinline__ float swz(float v) { return __int_as_float(__builtin_amdgcn_ds_swizzle(__float_as_int(v), (K << 10) | 0x1f)); }
; __device__ __forceinline__ float x32_sum(float v) { auto r = __builtin_amdgcn_permlane32_swap(__float_as_uint(v), __float_as_uint(v), false, false); return __uint_as_float(r[0]) + __uint_as_float(r[1]); }
; __device__ __forceinline__ unsigned cvt_pk_bf16(float lo, float hi) { const f32x2c f = {lo, hi}; return __builtin_bit_cast(unsigned, __builtin_convertvector(f, bf16x2c)); }
;     __device__ __forceinline__ void operator()(const f32x4 (&acc)[2][2][4][2], const Unit& u, int wr, int wc, int, int) const {
;     ...
;                 const int row = rowb + ai * HALF + m * 16;
;                 float ss = 0.f;
; #pragma unroll
;                 for (int j = 0; j < 4; ++j) ss += acc[ai][0][m][0][j] * acc[ai][0][m][0][j] + acc[ai][0][m][1][j] * acc[ai][0][m][1][j] + acc[ai][1][m][0][j] * acc[ai][1][m][0][j] + acc[ai][1][m][1][j] * acc[ai][1][m][1][j];
;                 ss += ::swz<16>(ss); ss = ::x32_sum(ss);
;                 float rs = rsqrtf(ss * inv_cnt + 1e-6f) * sc; rs = is_v ? 1.0f : rs;
;                 const int pos = row & 2047, pp = rot ? ((fq & 1) ? (pos & 63) : (pos >> 6)) : 0;
;                 const float* rt = rope + pp * 16;
;                 bf16_t* dst = obase + (unsigned)(row * ostride + ocol);
; #pragma unroll
;                 for (int n = 0; n < 2; ++n) {
;                     const f32x4 g1 = *(const f32x4*)(g + 4 * n), g2 = *(const f32x4*)(g + sbj + 4 * n);
;                     const f32x4 t0 = *(const f32x4*)(rt + 8 * n), t1 = *(const f32x4*)(rt + 8 * n + 4);
;                     const f32x4 c = (f32x4){t0[0], t0[2], t1[0], t1[2]}, s = (f32x4){t0[1], t0[3], t1[1], t1[3]};
;                     const f32x4 a1 = acc[ai][0][m][n] * rs * g1, a2 = acc[ai][1][m][n] * rs * g2;
;                     const f32x4 o1 = a1 * c - a2 * s, o2 = a1 * s + a2 * c;
;                     if (st_ok) { u32x2 w; w.x = cvt_pk_bf16(o1[0], o1[1]); w.y = cvt_pk_bf16(o1[2], o1[3]); *(u32x2*)(dst + 4 * n) = w;
;                         w.x = cvt_pk_bf16(o2[0], o2[1]); w.y = cvt_pk_bf16(o2[2], o2[3]); *(u32x2*)(dst + sbj + 4 * n) = w; }
;                 }
.LBB0_677:
	s_or_b64 exec, exec, s[2:3]
	v_mul_f32_e32 v66, v54, v54
	v_mul_f32_e32 v67, v55, v55
	v_fmac_f32_e32 v66, v62, v62
	v_fmac_f32_e32 v67, v63, v63
	v_fmac_f32_e32 v66, v58, v58
	v_fmac_f32_e32 v67, v59, v59
	v_fmac_f32_e32 v66, v50, v50
	v_fmac_f32_e32 v67, v51, v51
	v_add_f32_e32 v66, v66, v67
	v_mul_f32_e32 v67, v56, v56
	v_fmac_f32_e32 v67, v64, v64
	v_fmac_f32_e32 v67, v60, v60
	v_fmac_f32_e32 v67, v52, v52
	v_add_f32_e32 v66, v67, v66
	v_mul_f32_e32 v67, v57, v57
	v_fmac_f32_e32 v67, v65, v65
	v_fmac_f32_e32 v67, v61, v61
	v_fmac_f32_e32 v67, v53, v53
	v_add_f32_e32 v67, v67, v66
	ds_swizzle_b32 v68, v67 offset:swizzle(SWAP,16)
	v_add_u32_e32 v66, 0x80, v160
	v_bfe_u32 v71, v66, 6, 5
	s_waitcnt lgkmcnt(0)
	v_add_f32_e32 v70, v67, v68
	v_mov_b32_e32 v72, v70
	s_nop 1
	v_permlane32_swap_b32_e32 v70, v72
	s_and_saveexec_b64 s[2:3], s[20:21]
	v_add_f32_e32 v70, v70, v72
	v_mad_u64_u32 v[66:67], s[42:43], s26, v66, v[142:143]
	v_fmaak_f32 v70, v159, v70, 0x358637bd
	v_cmp_gt_f32_e64 s[42:43], s88, v70
	v_mul_f32_e32 v72, 0x4b800000, v70
	v_mov_b32_e32 v67, v0
	v_cndmask_b32_e64 v70, v70, v72, s[42:43]
	v_rsq_f32_e32 v70, v70
	v_lshl_add_u64 v[68:69], v[66:67], 1, s[60:61]
	s_lshl_b32 s54, s16, 1
	v_lshl_add_u64 v[66:67], v[68:69], 0, s[54:55]
	v_mul_f32_e32 v72, 0x45800000, v70
	v_cndmask_b32_e64 v70, v70, v72, s[42:43]
	v_cndmask_b32_e64 v72, v161, v71, s[40:41]
	v_mul_f32_e32 v70, v143, v70
	v_lshlrev_b32_e32 v72, 4, v72
	v_cndmask_b32_e64 v70, v70, 1.0, s[50:51]
	v_cndmask_b32_e32 v72, 0, v72, vcc
	v_lshlrev_b32_e32 v86, 2, v72
	global_load_dwordx4 v[172:175], v86, s[22:23]
	global_load_dwordx4 v[176:179], v86, s[22:23] offset:16
	global_load_dwordx4 v[180:183], v[140:141], off
	global_load_dwordx4 v[184:187], v[138:139], off offset:16
	global_load_dwordx4 v[188:191], v86, s[22:23] offset:32
	global_load_dwordx4 v[192:195], v86, s[22:23] offset:48
	global_load_dwordx4 v[196:199], v[140:141], off offset:16
	v_pk_mul_f32 v[72:73], v[64:65], v[70:71] op_sel_hi:[1,0]
	v_pk_mul_f32 v[74:75], v[62:63], v[70:71] op_sel_hi:[1,0]
	global_load_dwordx4 v[204:207], v[138:139], off
	v_pk_mul_f32 v[80:81], v[58:59], v[70:71] op_sel_hi:[1,0]
	v_pk_mul_f32 v[82:83], v[60:61], v[70:71] op_sel_hi:[1,0]
	s_waitcnt vmcnt(12)
	v_pk_mul_f32 v[76:77], v[74:75], v[200:201]
	v_pk_mul_f32 v[78:79], v[72:73], v[202:203]
	s_waitcnt vmcnt(6)
	v_mov_b32_e32 v84, v176
	s_waitcnt vmcnt(5)
	v_pk_mul_f32 v[60:61], v[82:83], v[182:183]
	v_pk_mul_f32 v[58:59], v[80:81], v[180:181]
	v_mov_b32_e32 v80, v172
	v_mov_b32_e32 v81, v174
	v_mov_b32_e32 v85, v178
	v_mov_b32_e32 v178, v177
	v_mov_b32_e32 v174, v173
	v_pk_mul_f32 v[82:83], v[80:81], v[58:59]
	v_pk_mul_f32 v[88:89], v[84:85], v[60:61]
	v_pk_mul_f32 v[58:59], v[174:175], v[58:59]
	v_pk_mul_f32 v[60:61], v[178:179], v[60:61]
	v_pk_fma_f32 v[58:59], v[76:77], v[80:81], v[58:59] neg_lo:[0,0,1] neg_hi:[0,0,1]
	v_pk_fma_f32 v[60:61], v[78:79], v[84:85], v[60:61] neg_lo:[0,0,1] neg_hi:[0,0,1]
	v_pk_fma_f32 v[72:73], v[78:79], v[178:179], v[88:89]
	v_pk_fma_f32 v[62:63], v[76:77], v[174:175], v[82:83]
	v_cvt_pk_bf16_f32 v58, v58, v59
	v_cvt_pk_bf16_f32 v59, v60, v61
	global_store_dwordx2 v[68:69], v[58:59], off
	v_cvt_pk_bf16_f32 v58, v62, v63
	v_cvt_pk_bf16_f32 v59, v72, v73
	global_store_dwordx2 v[66:67], v[58:59], off
	v_pk_mul_f32 v[58:59], v[56:57], v[70:71] op_sel_hi:[1,0]
	v_pk_mul_f32 v[60:61], v[54:55], v[70:71] op_sel_hi:[1,0]
	v_pk_mul_f32 v[72:73], v[50:51], v[70:71] op_sel_hi:[1,0]
	v_pk_mul_f32 v[74:75], v[52:53], v[70:71] op_sel_hi:[1,0]
	s_waitcnt vmcnt(6)
	v_pk_mul_f32 v[62:63], v[60:61], v[184:185]
	v_pk_mul_f32 v[64:65], v[58:59], v[186:187]
	s_waitcnt vmcnt(4)
	v_mov_b32_e32 v76, v192
	s_waitcnt vmcnt(3)
	v_pk_mul_f32 v[52:53], v[74:75], v[198:199]
	v_pk_mul_f32 v[50:51], v[72:73], v[196:197]
	v_mov_b32_e32 v72, v188
	v_mov_b32_e32 v73, v190
	v_mov_b32_e32 v77, v194
	v_mov_b32_e32 v194, v193
	v_mov_b32_e32 v190, v189
	v_pk_mul_f32 v[74:75], v[72:73], v[50:51]
	v_pk_mul_f32 v[78:79], v[76:77], v[52:53]
	v_pk_mul_f32 v[50:51], v[190:191], v[50:51]
	v_pk_mul_f32 v[52:53], v[194:195], v[52:53]
	v_pk_fma_f32 v[50:51], v[62:63], v[72:73], v[50:51] neg_lo:[0,0,1] neg_hi:[0,0,1]
	v_pk_fma_f32 v[52:53], v[64:65], v[76:77], v[52:53] neg_lo:[0,0,1] neg_hi:[0,0,1]
	v_pk_fma_f32 v[58:59], v[64:65], v[194:195], v[78:79]
	v_pk_fma_f32 v[54:55], v[62:63], v[190:191], v[74:75]
	v_cvt_pk_bf16_f32 v50, v50, v51
	v_cvt_pk_bf16_f32 v51, v52, v53
	global_store_dwordx2 v[68:69], v[50:51], off offset:8
	v_cvt_pk_bf16_f32 v50, v54, v55
	v_cvt_pk_bf16_f32 v51, v58, v59
	global_store_dwordx2 v[66:67], v[50:51], off offset:8
; template <int K> __device__ __forceinline__ float swz(float v) { return __int_as_float(__builtin_amdgcn_ds_swizzle(__float_as_int(v), (K << 10) | 0x1f)); }
; __device__ __forceinline__ float x32_sum(float v) { auto r = __builtin_amdgcn_permlane32_swap(__float_as_uint(v), __float_as_uint(v), false, false); return __uint_as_float(r[0]) + __uint_as_float(r[1]); }
; __device__ __forceinline__ unsigned cvt_pk_bf16(float lo, float hi) { const f32x2c f = {lo, hi}; return __builtin_bit_cast(unsigned, __builtin_convertvector(f, bf16x2c)); }
;     __device__ __forceinline__ void operator()(const f32x4 (&acc)[2][2][4][2], const Unit& u, int wr, int wc, int, int) const {
;     ...
;                 const int row = rowb + ai * HALF + m * 16;
;                 float ss = 0.f;
; #pragma unroll
;                 for (int j = 0; j < 4; ++j) ss += acc[ai][0][m][0][j] * acc[ai][0][m][0][j] + acc[ai][0][m][1][j] * acc[ai][0][m][1][j] + acc[ai][1][m][0][j] * acc[ai][1][m][0][j] + acc[ai][1][m][1][j] * acc[ai][1][m][1][j];
;                 ss += ::swz<16>(ss); ss = ::x32_sum(ss);
;                 float rs = rsqrtf(ss * inv_cnt + 1e-6f) * sc; rs = is_v ? 1.0f : rs;
;                 const int pos = row & 2047, pp = rot ? ((fq & 1) ? (pos & 63) : (pos >> 6)) : 0;
;                 const float* rt = rope + pp * 16;
;                 bf16_t* dst = obase + (unsigned)(row * ostride + ocol);
; #pragma unroll
;                 for (int n = 0; n < 2; ++n) {
;                     const f32x4 g1 = *(const f32x4*)(g + 4 * n), g2 = *(const f32x4*)(g + sbj + 4 * n);
;                     const f32x4 t0 = *(const f32x4*)(rt + 8 * n), t1 = *(const f32x4*)(rt + 8 * n + 4);
;                     const f32x4 c = (f32x4){t0[0], t0[2], t1[0], t1[2]}, s = (f32x4){t0[1], t0[3], t1[1], t1[3]};
;                     const f32x4 a1 = acc[ai][0][m][n] * rs * g1, a2 = acc[ai][1][m][n] * rs * g2;
;                     const f32x4 o1 = a1 * c - a2 * s, o2 = a1 * s + a2 * c;
;                     if (st_ok) { u32x2 w; w.x = cvt_pk_bf16(o1[0], o1[1]); w.y = cvt_pk_bf16(o1[2], o1[3]); *(u32x2*)(dst + 4 * n) = w;
;                         w.x = cvt_pk_bf16(o2[0], o2[1]); w.y = cvt_pk_bf16(o2[2], o2[3]); *(u32x2*)(dst + sbj + 4 * n) = w; }
;                 }
.LBB0_679:
	s_or_b64 exec, exec, s[2:3]
	v_mul_f32_e32 v50, v38, v38
	v_mul_f32_e32 v51, v39, v39
	v_fmac_f32_e32 v50, v46, v46
	v_fmac_f32_e32 v51, v47, v47
	v_fmac_f32_e32 v50, v42, v42
	v_fmac_f32_e32 v51, v43, v43
	v_fmac_f32_e32 v50, v34, v34
	v_fmac_f32_e32 v51, v35, v35
	v_add_f32_e32 v50, v50, v51
	v_mul_f32_e32 v51, v40, v40
	v_fmac_f32_e32 v51, v48, v48
	v_fmac_f32_e32 v51, v44, v44
	v_fmac_f32_e32 v51, v36, v36
	v_add_f32_e32 v50, v51, v50
	v_mul_f32_e32 v51, v41, v41
	v_fmac_f32_e32 v51, v49, v49
	v_fmac_f32_e32 v51, v45, v45
	v_fmac_f32_e32 v51, v37, v37
	v_add_f32_e32 v50, v51, v50
	ds_swizzle_b32 v51, v50 offset:swizzle(SWAP,16)
	s_waitcnt lgkmcnt(0)
	v_add_f32_e32 v54, v50, v51
	v_mov_b32_e32 v55, v54
	s_nop 1
	v_permlane32_swap_b32_e32 v54, v55
	s_and_saveexec_b64 s[2:3], s[20:21]
	v_add_u32_e32 v50, 0x90, v160
	v_add_f32_e32 v54, v54, v55
	v_mad_u64_u32 v[50:51], s[42:43], s26, v50, v[142:143]
	v_fmaak_f32 v54, v159, v54, 0x358637bd
	v_cmp_gt_f32_e64 s[42:43], s88, v54
	v_mul_f32_e32 v55, 0x4b800000, v54
	v_mov_b32_e32 v51, v0
	v_cndmask_b32_e64 v54, v54, v55, s[42:43]
	v_rsq_f32_e32 v54, v54
	v_lshl_add_u64 v[52:53], v[50:51], 1, s[60:61]
	s_lshl_b32 s54, s16, 1
	v_lshl_add_u64 v[50:51], v[52:53], 0, s[54:55]
	v_mul_f32_e32 v55, 0x45800000, v54
	v_cndmask_b32_e64 v54, v54, v55, s[42:43]
	v_cndmask_b32_e64 v55, v119, v71, s[40:41]
	v_lshlrev_b32_e32 v55, 4, v55
	v_mul_f32_e32 v54, v143, v54
	v_cndmask_b32_e32 v55, 0, v55, vcc
	v_cndmask_b32_e64 v54, v54, 1.0, s[50:51]
	v_lshlrev_b32_e32 v55, 2, v55
	global_load_dwordx4 v[172:175], v55, s[22:23]
	global_load_dwordx4 v[176:179], v55, s[22:23] offset:16
	global_load_dwordx4 v[180:183], v[140:141], off
	global_load_dwordx4 v[184:187], v[138:139], off offset:16
	global_load_dwordx4 v[188:191], v55, s[22:23] offset:32
	global_load_dwordx4 v[192:195], v55, s[22:23] offset:48
	global_load_dwordx4 v[196:199], v[140:141], off offset:16
	v_pk_mul_f32 v[56:57], v[48:49], v[54:55] op_sel_hi:[1,0]
	v_pk_mul_f32 v[58:59], v[46:47], v[54:55] op_sel_hi:[1,0]
	global_load_dwordx4 v[200:203], v[138:139], off
	v_pk_mul_f32 v[64:65], v[42:43], v[54:55] op_sel_hi:[1,0]
	v_pk_mul_f32 v[66:67], v[44:45], v[54:55] op_sel_hi:[1,0]
	s_waitcnt vmcnt(12)
	v_pk_mul_f32 v[60:61], v[58:59], v[204:205]
	v_pk_mul_f32 v[62:63], v[56:57], v[206:207]
	s_waitcnt vmcnt(6)
	v_mov_b32_e32 v68, v176
	s_waitcnt vmcnt(5)
	v_pk_mul_f32 v[44:45], v[66:67], v[182:183]
	v_pk_mul_f32 v[42:43], v[64:65], v[180:181]
	v_mov_b32_e32 v64, v172
	v_mov_b32_e32 v65, v174
	v_mov_b32_e32 v69, v178
	v_mov_b32_e32 v178, v177
	v_mov_b32_e32 v174, v173
	v_pk_mul_f32 v[66:67], v[64:65], v[42:43]
	v_pk_mul_f32 v[72:73], v[68:69], v[44:45]
	v_pk_mul_f32 v[42:43], v[174:175], v[42:43]
	v_pk_mul_f32 v[44:45], v[178:179], v[44:45]
	v_pk_fma_f32 v[42:43], v[60:61], v[64:65], v[42:43] neg_lo:[0,0,1] neg_hi:[0,0,1]
	v_pk_fma_f32 v[44:45], v[62:63], v[68:69], v[44:45] neg_lo:[0,0,1] neg_hi:[0,0,1]
	v_pk_fma_f32 v[56:57], v[62:63], v[178:179], v[72:73]
	v_pk_fma_f32 v[46:47], v[60:61], v[174:175], v[66:67]
	v_cvt_pk_bf16_f32 v42, v42, v43
	v_cvt_pk_bf16_f32 v43, v44, v45
	global_store_dwordx2 v[52:53], v[42:43], off
	v_cvt_pk_bf16_f32 v42, v46, v47
	v_cvt_pk_bf16_f32 v43, v56, v57
	global_store_dwordx2 v[50:51], v[42:43], off
	v_pk_mul_f32 v[42:43], v[40:41], v[54:55] op_sel_hi:[1,0]
	v_pk_mul_f32 v[44:45], v[38:39], v[54:55] op_sel_hi:[1,0]
	v_pk_mul_f32 v[56:57], v[34:35], v[54:55] op_sel_hi:[1,0]
	s_waitcnt vmcnt(6)
	v_pk_mul_f32 v[46:47], v[44:45], v[184:185]
	v_pk_mul_f32 v[48:49], v[42:43], v[186:187]
	v_pk_mul_f32 v[54:55], v[36:37], v[54:55] op_sel_hi:[1,0]
	s_waitcnt vmcnt(4)
	v_mov_b32_e32 v58, v192
	v_mov_b32_e32 v59, v194
	s_waitcnt vmcnt(3)
	v_pk_mul_f32 v[36:37], v[54:55], v[198:199]
	v_pk_mul_f32 v[34:35], v[56:57], v[196:197]
	v_mov_b32_e32 v54, v188
	v_mov_b32_e32 v55, v190
	v_mov_b32_e32 v194, v193
	v_mov_b32_e32 v190, v189
	v_pk_mul_f32 v[56:57], v[54:55], v[34:35]
	v_pk_mul_f32 v[60:61], v[58:59], v[36:37]
	v_pk_mul_f32 v[34:35], v[190:191], v[34:35]
	v_pk_mul_f32 v[36:37], v[194:195], v[36:37]
	v_pk_fma_f32 v[34:35], v[46:47], v[54:55], v[34:35] neg_lo:[0,0,1] neg_hi:[0,0,1]
	v_pk_fma_f32 v[36:37], v[48:49], v[58:59], v[36:37] neg_lo:[0,0,1] neg_hi:[0,0,1]
	v_pk_fma_f32 v[42:43], v[48:49], v[194:195], v[60:61]
	v_pk_fma_f32 v[38:39], v[46:47], v[190:191], v[56:57]
	v_cvt_pk_bf16_f32 v34, v34, v35
	v_cvt_pk_bf16_f32 v35, v36, v37
	global_store_dwordx2 v[52:53], v[34:35], off offset:8
	v_cvt_pk_bf16_f32 v34, v38, v39
	v_cvt_pk_bf16_f32 v35, v42, v43
	global_store_dwordx2 v[50:51], v[34:35], off offset:8
; template <int K> __device__ __forceinline__ float swz(float v) { return __int_as_float(__builtin_amdgcn_ds_swizzle(__float_as_int(v), (K << 10) | 0x1f)); }
; __device__ __forceinline__ float x32_sum(float v) { auto r = __builtin_amdgcn_permlane32_swap(__float_as_uint(v), __float_as_uint(v), false, false); return __uint_as_float(r[0]) + __uint_as_float(r[1]); }
; __device__ __forceinline__ unsigned cvt_pk_bf16(float lo, float hi) { const f32x2c f = {lo, hi}; return __builtin_bit_cast(unsigned, __builtin_convertvector(f, bf16x2c)); }
;     __device__ __forceinline__ void operator()(const f32x4 (&acc)[2][2][4][2], const Unit& u, int wr, int wc, int, int) const {
;     ...
;                 const int row = rowb + ai * HALF + m * 16;
;                 float ss = 0.f;
; #pragma unroll
;                 for (int j = 0; j < 4; ++j) ss += acc[ai][0][m][0][j] * acc[ai][0][m][0][j] + acc[ai][0][m][1][j] * acc[ai][0][m][1][j] + acc[ai][1][m][0][j] * acc[ai][1][m][0][j] + acc[ai][1][m][1][j] * acc[ai][1][m][1][j];
;                 ss += ::swz<16>(ss); ss = ::x32_sum(ss);
;                 float rs = rsqrtf(ss * inv_cnt + 1e-6f) * sc; rs = is_v ? 1.0f : rs;
;                 const int pos = row & 2047, pp = rot ? ((fq & 1) ? (pos & 63) : (pos >> 6)) : 0;
;                 const float* rt = rope + pp * 16;
;                 bf16_t* dst = obase + (unsigned)(row * ostride + ocol);
; #pragma unroll
;                 for (int n = 0; n < 2; ++n) {
;                     const f32x4 g1 = *(const f32x4*)(g + 4 * n), g2 = *(const f32x4*)(g + sbj + 4 * n);
;                     const f32x4 t0 = *(const f32x4*)(rt + 8 * n), t1 = *(const f32x4*)(rt + 8 * n + 4);
;                     const f32x4 c = (f32x4){t0[0], t0[2], t1[0], t1[2]}, s = (f32x4){t0[1], t0[3], t1[1], t1[3]};
;                     const f32x4 a1 = acc[ai][0][m][n] * rs * g1, a2 = acc[ai][1][m][n] * rs * g2;
;                     const f32x4 o1 = a1 * c - a2 * s, o2 = a1 * s + a2 * c;
;                     if (st_ok) { u32x2 w; w.x = cvt_pk_bf16(o1[0], o1[1]); w.y = cvt_pk_bf16(o1[2], o1[3]); *(u32x2*)(dst + 4 * n) = w;
;                         w.x = cvt_pk_bf16(o2[0], o2[1]); w.y = cvt_pk_bf16(o2[2], o2[3]); *(u32x2*)(dst + sbj + 4 * n) = w; }
;                 }
.LBB0_681:
	s_or_b64 exec, exec, s[2:3]
	v_mul_f32_e32 v34, v22, v22
	v_mul_f32_e32 v35, v23, v23
	v_fmac_f32_e32 v34, v30, v30
	v_fmac_f32_e32 v35, v31, v31
	v_fmac_f32_e32 v34, v26, v26
	v_fmac_f32_e32 v35, v27, v27
	v_fmac_f32_e32 v34, v18, v18
	v_fmac_f32_e32 v35, v19, v19
	v_add_f32_e32 v34, v34, v35
	v_mul_f32_e32 v35, v24, v24
	v_fmac_f32_e32 v35, v32, v32
	v_fmac_f32_e32 v35, v28, v28
	v_fmac_f32_e32 v35, v20, v20
	v_add_f32_e32 v34, v35, v34
	v_mul_f32_e32 v35, v25, v25
	v_fmac_f32_e32 v35, v33, v33
	v_fmac_f32_e32 v35, v29, v29
	v_fmac_f32_e32 v35, v21, v21
	v_add_f32_e32 v34, v35, v34
	ds_swizzle_b32 v35, v34 offset:swizzle(SWAP,16)
	s_waitcnt lgkmcnt(0)
	v_add_f32_e32 v38, v34, v35
	v_mov_b32_e32 v39, v38
	s_nop 1
	v_permlane32_swap_b32_e32 v38, v39
	s_and_saveexec_b64 s[2:3], s[20:21]
	v_add_u32_e32 v34, 0xa0, v160
	v_add_f32_e32 v38, v38, v39
	v_mad_u64_u32 v[34:35], s[42:43], s26, v34, v[142:143]
	v_fmaak_f32 v38, v159, v38, 0x358637bd
	v_cmp_gt_f32_e64 s[42:43], s88, v38
	v_mul_f32_e32 v39, 0x4b800000, v38
	v_mov_b32_e32 v35, v0
	v_cndmask_b32_e64 v38, v38, v39, s[42:43]
	v_rsq_f32_e32 v38, v38
	v_lshl_add_u64 v[36:37], v[34:35], 1, s[60:61]
	s_lshl_b32 s54, s16, 1
	v_lshl_add_u64 v[34:35], v[36:37], 0, s[54:55]
	v_mul_f32_e32 v39, 0x45800000, v38
	v_cndmask_b32_e64 v38, v38, v39, s[42:43]
	v_cndmask_b32_e64 v39, v103, v71, s[40:41]
	v_lshlrev_b32_e32 v39, 4, v39
	v_mul_f32_e32 v38, v143, v38
	v_cndmask_b32_e32 v39, 0, v39, vcc
	v_cndmask_b32_e64 v38, v38, 1.0, s[50:51]
	v_lshlrev_b32_e32 v39, 2, v39
	global_load_dwordx4 v[172:175], v39, s[22:23]
	global_load_dwordx4 v[176:179], v39, s[22:23] offset:16
	global_load_dwordx4 v[180:183], v[140:141], off
	global_load_dwordx4 v[184:187], v[138:139], off offset:16
	global_load_dwordx4 v[188:191], v39, s[22:23] offset:32
	global_load_dwordx4 v[192:195], v39, s[22:23] offset:48
	global_load_dwordx4 v[196:199], v[140:141], off offset:16
	v_pk_mul_f32 v[40:41], v[32:33], v[38:39] op_sel_hi:[1,0]
	v_pk_mul_f32 v[42:43], v[30:31], v[38:39] op_sel_hi:[1,0]
	global_load_dwordx4 v[204:207], v[138:139], off
	v_pk_mul_f32 v[48:49], v[26:27], v[38:39] op_sel_hi:[1,0]
	v_pk_mul_f32 v[50:51], v[28:29], v[38:39] op_sel_hi:[1,0]
	s_waitcnt vmcnt(12)
	v_pk_mul_f32 v[44:45], v[42:43], v[200:201]
	v_pk_mul_f32 v[46:47], v[40:41], v[202:203]
	s_waitcnt vmcnt(6)
	v_mov_b32_e32 v52, v176
	s_waitcnt vmcnt(5)
	v_pk_mul_f32 v[28:29], v[50:51], v[182:183]
	v_pk_mul_f32 v[26:27], v[48:49], v[180:181]
	v_mov_b32_e32 v48, v172
	v_mov_b32_e32 v49, v174
	v_mov_b32_e32 v53, v178
	v_mov_b32_e32 v178, v177
	v_mov_b32_e32 v174, v173
	v_pk_mul_f32 v[50:51], v[48:49], v[26:27]
	v_pk_mul_f32 v[54:55], v[52:53], v[28:29]
	v_pk_mul_f32 v[26:27], v[174:175], v[26:27]
	v_pk_mul_f32 v[28:29], v[178:179], v[28:29]
	v_pk_fma_f32 v[26:27], v[44:45], v[48:49], v[26:27] neg_lo:[0,0,1] neg_hi:[0,0,1]
	v_pk_fma_f32 v[28:29], v[46:47], v[52:53], v[28:29] neg_lo:[0,0,1] neg_hi:[0,0,1]
	v_pk_fma_f32 v[40:41], v[46:47], v[178:179], v[54:55]
	v_pk_fma_f32 v[30:31], v[44:45], v[174:175], v[50:51]
	v_cvt_pk_bf16_f32 v26, v26, v27
	v_cvt_pk_bf16_f32 v27, v28, v29
	global_store_dwordx2 v[36:37], v[26:27], off
	v_cvt_pk_bf16_f32 v26, v30, v31
	v_cvt_pk_bf16_f32 v27, v40, v41
	global_store_dwordx2 v[34:35], v[26:27], off
	v_pk_mul_f32 v[26:27], v[24:25], v[38:39] op_sel_hi:[1,0]
	v_pk_mul_f32 v[28:29], v[22:23], v[38:39] op_sel_hi:[1,0]
	v_pk_mul_f32 v[40:41], v[18:19], v[38:39] op_sel_hi:[1,0]
	s_waitcnt vmcnt(6)
	v_pk_mul_f32 v[30:31], v[28:29], v[184:185]
	v_pk_mul_f32 v[32:33], v[26:27], v[186:187]
	v_pk_mul_f32 v[38:39], v[20:21], v[38:39] op_sel_hi:[1,0]
	s_waitcnt vmcnt(4)
	v_mov_b32_e32 v42, v192
	v_mov_b32_e32 v43, v194
	s_waitcnt vmcnt(3)
	v_pk_mul_f32 v[20:21], v[38:39], v[198:199]
	v_pk_mul_f32 v[18:19], v[40:41], v[196:197]
	v_mov_b32_e32 v38, v188
	v_mov_b32_e32 v39, v190
	v_mov_b32_e32 v194, v193
	v_mov_b32_e32 v190, v189
	v_pk_mul_f32 v[40:41], v[38:39], v[18:19]
	v_pk_mul_f32 v[44:45], v[42:43], v[20:21]
	v_pk_mul_f32 v[18:19], v[190:191], v[18:19]
	v_pk_mul_f32 v[20:21], v[194:195], v[20:21]
	v_pk_fma_f32 v[18:19], v[30:31], v[38:39], v[18:19] neg_lo:[0,0,1] neg_hi:[0,0,1]
	v_pk_fma_f32 v[20:21], v[32:33], v[42:43], v[20:21] neg_lo:[0,0,1] neg_hi:[0,0,1]
	v_pk_fma_f32 v[26:27], v[32:33], v[194:195], v[44:45]
	v_pk_fma_f32 v[22:23], v[30:31], v[190:191], v[40:41]
	v_cvt_pk_bf16_f32 v18, v18, v19
	v_cvt_pk_bf16_f32 v19, v20, v21
	global_store_dwordx2 v[36:37], v[18:19], off offset:8
	v_cvt_pk_bf16_f32 v18, v22, v23
	v_cvt_pk_bf16_f32 v19, v26, v27
	global_store_dwordx2 v[34:35], v[18:19], off offset:8
; template <int K> __device__ __forceinline__ float swz(float v) { return __int_as_float(__builtin_amdgcn_ds_swizzle(__float_as_int(v), (K << 10) | 0x1f)); }
; __device__ __forceinline__ float x32_sum(float v) { auto r = __builtin_amdgcn_permlane32_swap(__float_as_uint(v), __float_as_uint(v), false, false); return __uint_as_float(r[0]) + __uint_as_float(r[1]); }
; __device__ __forceinline__ unsigned cvt_pk_bf16(float lo, float hi) { const f32x2c f = {lo, hi}; return __builtin_bit_cast(unsigned, __builtin_convertvector(f, bf16x2c)); }
;     __device__ __forceinline__ void operator()(const f32x4 (&acc)[2][2][4][2], const Unit& u, int wr, int wc, int, int) const {
;     ...
;                 const int row = rowb + ai * HALF + m * 16;
;                 float ss = 0.f;
; #pragma unroll
;                 for (int j = 0; j < 4; ++j) ss += acc[ai][0][m][0][j] * acc[ai][0][m][0][j] + acc[ai][0][m][1][j] * acc[ai][0][m][1][j] + acc[ai][1][m][0][j] * acc[ai][1][m][0][j] + acc[ai][1][m][1][j] * acc[ai][1][m][1][j];
;                 ss += ::swz<16>(ss); ss = ::x32_sum(ss);
;                 float rs = rsqrtf(ss * inv_cnt + 1e-6f) * sc; rs = is_v ? 1.0f : rs;
;                 const int pos = row & 2047, pp = rot ? ((fq & 1) ? (pos & 63) : (pos >> 6)) : 0;
;                 const float* rt = rope + pp * 16;
;                 bf16_t* dst = obase + (unsigned)(row * ostride + ocol);
; #pragma unroll
;                 for (int n = 0; n < 2; ++n) {
;                     const f32x4 g1 = *(const f32x4*)(g + 4 * n), g2 = *(const f32x4*)(g + sbj + 4 * n);
;                     const f32x4 t0 = *(const f32x4*)(rt + 8 * n), t1 = *(const f32x4*)(rt + 8 * n + 4);
;                     const f32x4 c = (f32x4){t0[0], t0[2], t1[0], t1[2]}, s = (f32x4){t0[1], t0[3], t1[1], t1[3]};
;                     const f32x4 a1 = acc[ai][0][m][n] * rs * g1, a2 = acc[ai][1][m][n] * rs * g2;
;                     const f32x4 o1 = a1 * c - a2 * s, o2 = a1 * s + a2 * c;
;                     if (st_ok) { u32x2 w; w.x = cvt_pk_bf16(o1[0], o1[1]); w.y = cvt_pk_bf16(o1[2], o1[3]); *(u32x2*)(dst + 4 * n) = w;
;                         w.x = cvt_pk_bf16(o2[0], o2[1]); w.y = cvt_pk_bf16(o2[2], o2[3]); *(u32x2*)(dst + sbj + 4 * n) = w; }
;                 }
.LBB0_683:
	s_or_b64 exec, exec, s[2:3]
	v_mul_f32_e32 v18, v6, v6
	v_mul_f32_e32 v19, v7, v7
	v_fmac_f32_e32 v18, v14, v14
	v_fmac_f32_e32 v19, v15, v15
	v_fmac_f32_e32 v18, v10, v10
	v_fmac_f32_e32 v19, v11, v11
	v_fmac_f32_e32 v18, v2, v2
	v_fmac_f32_e32 v19, v3, v3
	v_add_f32_e32 v18, v18, v19
	v_mul_f32_e32 v19, v8, v8
	v_fmac_f32_e32 v19, v16, v16
	v_fmac_f32_e32 v19, v12, v12
	v_fmac_f32_e32 v19, v4, v4
	v_add_f32_e32 v18, v19, v18
	v_mul_f32_e32 v19, v9, v9
	v_fmac_f32_e32 v19, v17, v17
	v_fmac_f32_e32 v19, v13, v13
	v_fmac_f32_e32 v19, v5, v5
	v_add_f32_e32 v18, v19, v18
	ds_swizzle_b32 v19, v18 offset:swizzle(SWAP,16)
	s_waitcnt lgkmcnt(0)
	v_add_f32_e32 v22, v18, v19
	v_mov_b32_e32 v23, v22
	s_nop 1
	v_permlane32_swap_b32_e32 v22, v23
	s_and_saveexec_b64 s[2:3], s[20:21]
	v_add_f32_e32 v22, v22, v23
	v_fmaak_f32 v22, v159, v22, 0x358637bd
	v_cmp_gt_f32_e64 s[42:43], s88, v22
	v_mul_f32_e32 v23, 0x4b800000, v22
	v_add_u32_e32 v18, 0xb0, v160
	v_cndmask_b32_e64 v22, v22, v23, s[42:43]
	v_rsq_f32_e32 v22, v22
	v_mad_u64_u32 v[18:19], s[20:21], s26, v18, v[142:143]
	v_mov_b32_e32 v19, v0
	v_mul_f32_e32 v23, 0x45800000, v22
	v_cndmask_b32_e64 v22, v22, v23, s[42:43]
	v_cndmask_b32_e64 v23, v87, v71, s[40:41]
	v_lshlrev_b32_e32 v23, 4, v23
	v_mul_f32_e32 v22, v143, v22
	v_cndmask_b32_e32 v23, 0, v23, vcc
	v_cndmask_b32_e64 v22, v22, 1.0, s[50:51]
	v_lshlrev_b32_e32 v23, 2, v23
	global_load_dwordx4 v[172:175], v23, s[22:23]
	global_load_dwordx4 v[176:179], v23, s[22:23] offset:16
	global_load_dwordx4 v[180:183], v[140:141], off
	global_load_dwordx4 v[184:187], v[138:139], off offset:16
	global_load_dwordx4 v[188:191], v23, s[22:23] offset:32
	global_load_dwordx4 v[192:195], v23, s[22:23] offset:48
	global_load_dwordx4 v[196:199], v[140:141], off offset:16
	v_pk_mul_f32 v[24:25], v[16:17], v[22:23] op_sel_hi:[1,0]
	v_pk_mul_f32 v[26:27], v[14:15], v[22:23] op_sel_hi:[1,0]
	v_pk_mul_f32 v[32:33], v[10:11], v[22:23] op_sel_hi:[1,0]
	v_pk_mul_f32 v[34:35], v[12:13], v[22:23] op_sel_hi:[1,0]
	v_lshl_add_u64 v[20:21], v[18:19], 1, s[60:61]
	s_lshl_b32 s54, s16, 1
	v_lshl_add_u64 v[18:19], v[20:21], 0, s[54:55]
	s_waitcnt vmcnt(11)
	v_pk_mul_f32 v[28:29], v[26:27], v[204:205]
	v_pk_mul_f32 v[30:31], v[24:25], v[206:207]
	s_waitcnt vmcnt(5)
	v_mov_b32_e32 v36, v176
	s_waitcnt vmcnt(4)
	v_pk_mul_f32 v[12:13], v[34:35], v[182:183]
	v_pk_mul_f32 v[10:11], v[32:33], v[180:181]
	v_mov_b32_e32 v32, v172
	v_mov_b32_e32 v33, v174
	v_mov_b32_e32 v37, v178
	v_mov_b32_e32 v178, v177
	v_mov_b32_e32 v174, v173
	v_pk_mul_f32 v[34:35], v[32:33], v[10:11]
	v_pk_mul_f32 v[38:39], v[36:37], v[12:13]
	v_pk_mul_f32 v[10:11], v[174:175], v[10:11]
	v_pk_mul_f32 v[12:13], v[178:179], v[12:13]
	v_pk_fma_f32 v[10:11], v[28:29], v[32:33], v[10:11] neg_lo:[0,0,1] neg_hi:[0,0,1]
	v_pk_fma_f32 v[12:13], v[30:31], v[36:37], v[12:13] neg_lo:[0,0,1] neg_hi:[0,0,1]
	v_pk_fma_f32 v[24:25], v[30:31], v[178:179], v[38:39]
	v_pk_fma_f32 v[14:15], v[28:29], v[174:175], v[34:35]
	v_cvt_pk_bf16_f32 v10, v10, v11
	v_cvt_pk_bf16_f32 v11, v12, v13
	global_store_dwordx2 v[20:21], v[10:11], off
	v_cvt_pk_bf16_f32 v10, v14, v15
	v_cvt_pk_bf16_f32 v11, v24, v25
	global_store_dwordx2 v[18:19], v[10:11], off
	v_pk_mul_f32 v[10:11], v[8:9], v[22:23] op_sel_hi:[1,0]
	v_pk_mul_f32 v[12:13], v[6:7], v[22:23] op_sel_hi:[1,0]
	v_pk_mul_f32 v[24:25], v[2:3], v[22:23] op_sel_hi:[1,0]
	s_waitcnt vmcnt(5)
	v_pk_mul_f32 v[14:15], v[12:13], v[184:185]
	v_pk_mul_f32 v[16:17], v[10:11], v[186:187]
	v_pk_mul_f32 v[22:23], v[4:5], v[22:23] op_sel_hi:[1,0]
	s_waitcnt vmcnt(3)
	v_mov_b32_e32 v26, v192
	v_mov_b32_e32 v27, v194
	s_waitcnt vmcnt(2)
	v_pk_mul_f32 v[4:5], v[22:23], v[198:199]
	v_pk_mul_f32 v[2:3], v[24:25], v[196:197]
	v_mov_b32_e32 v22, v188
	v_mov_b32_e32 v23, v190
	v_mov_b32_e32 v194, v193
	v_mov_b32_e32 v190, v189
	v_pk_mul_f32 v[24:25], v[22:23], v[2:3]
	v_pk_mul_f32 v[28:29], v[26:27], v[4:5]
	v_pk_mul_f32 v[2:3], v[190:191], v[2:3]
	v_pk_mul_f32 v[4:5], v[194:195], v[4:5]
	v_pk_fma_f32 v[2:3], v[14:15], v[22:23], v[2:3] neg_lo:[0,0,1] neg_hi:[0,0,1]
	v_pk_fma_f32 v[4:5], v[16:17], v[26:27], v[4:5] neg_lo:[0,0,1] neg_hi:[0,0,1]
	v_pk_fma_f32 v[10:11], v[16:17], v[194:195], v[28:29]
	v_pk_fma_f32 v[6:7], v[14:15], v[190:191], v[24:25]
	v_cvt_pk_bf16_f32 v2, v2, v3
	v_cvt_pk_bf16_f32 v3, v4, v5
	global_store_dwordx2 v[20:21], v[2:3], off offset:8
	v_cvt_pk_bf16_f32 v2, v6, v7
	v_cvt_pk_bf16_f32 v3, v10, v11
	global_store_dwordx2 v[18:19], v[2:3], off offset:8
	s_branch .LBB0_650

; template <int DQK>
; __device__ __forceinline__ void flash_item(unsigned char* smem, const bf16_t* Q, int qs, const bf16_t* K0, const bf16_t* V0, int n0, const bf16_t* K1, const bf16_t* V1, int n1, int ks, int vs, bf16_t* Oo, int os, float shift) {
;     ...
;     const int tid = otid(), lane = tid & 63, wave = tid >> 6, fr = lane & 15, fq = lane >> 4;
;     LASP unsigned char* ls = (LASP unsigned char*)smem;
;     bf16x8_t qf[2][NKK];
; #pragma unroll
;     for (int qg = 0; qg < 2; ++qg)
; #pragma unroll
;         for (int kk = 0; kk < NKK; ++kk) qf[qg][kk] = *(const bf16x8_t*)(Q + (size_t)(wave * 32 + qg * 16 + fr) * qs + kk * 32 + fq * 8);
;     f32x4_t o[4][2];
; #pragma unroll
; __device__ __forceinline__ void p4_attn(const Params& P, int l, bool last, unsigned char* smem) {
;     ...
;             const int i = __builtin_amdgcn_readfirstlane((int)*slot);
;             if (i >= nq) break;
;             unsigned char* ws = PWS;
;             const bf16_t* U = (const bf16_t*)(ws + WS_U);
;             bf16_t* O = (bf16_t*)(ws + WS_AO);
;             if (i >= 96 && i < 192) {
;                 const int j = i - 96, bp = q * 6 + (j >> 4), r = j & 15;
;                 na_item(smem, U, PIN(11) + (size_t)l * 6 * 15 * 31, O, bp / 3, r, bp % 3, shift_nal);
;             } else if (i >= 204) {
;                 const int bh = q * 12 + (i - 204), b = bh / 6, h = bh % 6;
;                 const size_t c0 = (size_t)NLAT + b * CTXL;
;                 flash_item<64>(smem, U + c0 * NINP + OQ + h * 64, NINP, U + c0 * NINP + OKK + h * 64, U + c0 * NINP + OV + h * 64, CTXL, nullptr, nullptr, 0, NINP, NINP, O + c0 * OW + h * 64, OW, shift_nac);
;             } else {
;                 const bf16_t* MQ = (const bf16_t*)(ws + WS_MQ); const bf16_t* MK = (const bf16_t*)(ws + WS_MK); const bf16_t* MV = (const bf16_t*)(ws + WS_MV);
;                 const bool lat = i < 96;
;                 const int bh = q * 12 + (lat ? (i >> 3) : (i - 192)), b = bh / 6, h = bh % 6;
;                 const size_t c0 = (size_t)NLAT + b * CTXL, l0 = (size_t)b * SEQ;
;                 const size_t q0 = lat ? l0 + (i & 7) * 256 : c0;
;                 flash_item<96>(smem, MQ + q0 * 576 + h * 96, 576, MK + c0 * 576 + h * 96, MV + c0 * 384 + h * 64, CTXL, MK + l0 * 576 + h * 96, MV + l0 * 384 + h * 64, lat ? SEQ : 0, 576, 384,
;                                O + q0 * OW + 384 + h * 64, OW, shift_mla);
.LBB0_827:
	s_or_b64 exec, exec, s[2:3]
	v_mov_b32_e32 v1, s94
	s_waitcnt lgkmcnt(0)
	s_barrier
	ds_read_b32 v1, v1
	s_mov_b64 s[2:3], -1
	s_waitcnt lgkmcnt(0)
	v_readfirstlane_b32 s13, v1
	s_cmp_ge_i32 s13, s7
	s_cbranch_scc1 .LBB0_822
	s_add_i32 s26, s13, 0xffffffa0
	s_cmpk_gt_u32 s26, 0x5f
	s_cbranch_scc0 .LBB0_838
	s_cmpk_lt_i32 s13, 0xcc
	s_cbranch_scc0 .LBB0_835
	s_ashr_i32 s2, s13, 3
	s_add_i32 s3, s13, 0xffffff40
	s_cmpk_lt_i32 s13, 0x60
	s_cselect_b32 s2, s2, s3
	s_cselect_b32 s27, 18, 2
	s_add_i32 s5, s2, s10
	s_mul_hi_i32 s2, s5, 0x2aaaaaab
	s_lshr_b32 s3, s2, 31
	s_add_i32 s2, s2, s3
	s_lshl_b32 s3, s2, 8
	s_ashr_i32 s16, s3, 31
	s_add_u32 s20, s3, 0x8000
	s_addc_u32 s21, s16, 0
	s_ashr_i32 s3, s2, 31
	s_lshl_b64 s[16:17], s[2:3], 11
	s_lshl_b32 s3, s13, 8
	s_and_b32 s3, s3, 0x700
	s_or_b32 s3, s16, s3
	s_cmpk_lt_i32 s13, 0x60
	s_mul_i32 s16, s2, 6
	s_cselect_b32 s28, s17, s21
	s_cselect_b32 s3, s3, s20
	s_sub_i32 s5, s5, s16
	s_mul_i32 s16, s28, 0x480
	s_mul_hi_u32 s17, s3, 0x480
	s_add_i32 s17, s17, s16
	s_mul_i32 s18, s3, 0x480
	s_mul_i32 s16, s5, 0x60
	s_add_u32 s18, s59, s18
	s_addc_u32 s19, s80, s17
	s_ashr_i32 s17, s16, 31
	s_lshl_b64 s[16:17], s[16:17], 1
	s_mul_hi_u32 s29, s20, 0x480
	s_mul_i32 s38, s21, 0x480
	s_add_u32 s18, s18, s16
	s_addc_u32 s19, s19, s17
	s_add_i32 s29, s29, s38
	s_mul_i32 s38, s20, 0x480
	s_add_u32 s38, s70, s38
	s_addc_u32 s29, s71, s29
	s_mul_hi_u32 s40, s20, 0x300
	s_mulk_i32 s21, 0x300
	s_add_u32 s38, s38, s16
	s_addc_u32 s39, s29, s17
	s_add_i32 s40, s40, s21
	s_mulk_i32 s20, 0x300
	s_add_u32 s29, s81, s20
	s_addc_u32 s41, s82, s40
	s_lshl_b32 s20, s5, 6
	s_ashr_i32 s21, s20, 31
	v_mov_b32_e32 v126, v253
	s_lshl_b64 s[20:21], s[20:21], 1
	v_lshlrev_b32_e32 v1, 3, v126
	s_add_u32 s40, s29, s20
	v_ashrrev_i32_e32 v127, 2, v126
	s_waitcnt vmcnt(8)
	v_and_b32_e32 v55, 24, v1
	v_lshlrev_b32_e32 v1, 4, v126
	v_mov_b64_e32 v[2:3], s[38:39]
	s_addc_u32 s41, s41, s21
	v_ashrrev_i32_e32 v129, 3, v126
	v_and_b32_e32 v22, 0x70, v1
	v_mov_b32_e32 v23, v0
	v_mad_i64_i32 v[2:3], s[38:39], v127, s91, v[2:3]
	v_lshlrev_b32_e32 v4, 1, v55
	v_mov_b32_e32 v5, v0
	v_add_u32_e32 v54, 64, v129
	v_lshl_add_u64 v[50:51], s[40:41], 0, v[22:23]
	v_lshl_add_u64 v[52:53], v[2:3], 0, v[4:5]
	v_mad_i64_i32 v[14:15], s[40:41], v54, s87, v[50:51]
	global_load_dwordx4 v[2:5], v[52:53], off offset:64
	global_load_dwordx4 v[6:9], v[52:53], off
	v_mad_i64_i32 v[16:17], s[38:39], v129, s87, v[50:51]
	global_load_dwordx4 v[10:13], v[52:53], off offset:128
	global_load_dwordx4 v[38:41], v[16:17], off
	global_load_dwordx4 v[42:45], v[14:15], off
	v_and_b32_e32 v130, 15, v126
	v_ashrrev_i32_e32 v14, 1, v126
	v_bfe_u32 v120, v126, 4, 2
	v_and_or_b32 v144, v14, s95, v130
	v_lshlrev_b32_e32 v24, 4, v120
	v_mov_b32_e32 v25, v0
	v_lshl_add_u64 v[18:19], s[18:19], 0, v[24:25]
	v_or_b32_e32 v142, 16, v144
	v_mad_i64_i32 v[34:35], s[18:19], v144, s91, v[18:19]
	v_mad_i64_i32 v[30:31], s[18:19], v142, s91, v[18:19]
	global_load_dwordx4 v[14:17], v[34:35], off
	global_load_dwordx4 v[18:21], v[30:31], off
	v_mul_lo_u32 v23, v127, s96
	v_and_b32_e32 v1, 48, v1
	v_mul_lo_u32 v25, v129, s89
	v_add_u32_e32 v23, 0, v23
	v_add_u32_e32 v22, 0, v22
	v_add_u32_e32 v128, 0, v24
	v_add_u32_e32 v1, v23, v1
	v_add_u32_e32 v143, v22, v25
	global_load_dwordx4 v[22:25], v[34:35], off offset:64
	global_load_dwordx4 v[26:29], v[30:31], off offset:128
	s_nop 0
	global_load_dwordx4 v[30:33], v[30:31], off offset:64
	s_nop 0
	global_load_dwordx4 v[34:37], v[34:35], off offset:128
	v_mad_u32_u24 v121, v130, s96, v128
	s_barrier
	v_lshlrev_b32_e32 v145, 2, v120
	v_add_u32_e32 v131, 0, v55
	s_mov_b32 s5, 0x24000
	s_mul_i32 s38, s2, 0x240000
	s_mov_b32 s29, 1
	s_waitcnt vmcnt(9)
	ds_write_b128 v1, v[6:9]
	ds_write_b128 v1, v[2:5] offset:64
	s_waitcnt vmcnt(8)
	ds_write_b128 v1, v[10:13] offset:128
	s_waitcnt vmcnt(7)
	ds_write_b128 v143, v[38:41] offset:32768
	s_waitcnt vmcnt(6)
	ds_write_b128 v143, v[42:45] offset:41984
	s_waitcnt lgkmcnt(0)
	s_barrier
	ds_read_b128 v[2:5], v121
	ds_read_b128 v[10:13], v121 offset:3328
	ds_read_b128 v[46:49], v121 offset:6656
	ds_read_b128 v[56:59], v121 offset:9984
	ds_read_b128 v[68:71], v121 offset:13312
	ds_read_b128 v[72:75], v121 offset:16640
	ds_read_b128 v[84:87], v121 offset:19968
	ds_read_b128 v[88:91], v121 offset:23296
	v_mov_b64_e32 v[6:7], s[44:45]
	v_mov_b64_e32 v[8:9], s[46:47]
	s_waitcnt vmcnt(5) lgkmcnt(7)
	s_nop 0
	v_mfma_f32_16x16x32_bf16 v[38:41], v[2:5], v[14:17], v[6:9]
	s_waitcnt vmcnt(4)
	v_mfma_f32_16x16x32_bf16 v[2:5], v[2:5], v[18:21], v[6:9]
	s_waitcnt lgkmcnt(6)
	v_mfma_f32_16x16x32_bf16 v[42:45], v[10:13], v[14:17], v[6:9]
	v_mfma_f32_16x16x32_bf16 v[10:13], v[10:13], v[18:21], v[6:9]
	s_waitcnt lgkmcnt(5)
	v_mfma_f32_16x16x32_bf16 v[60:63], v[46:49], v[14:17], v[6:9]
	v_mfma_f32_16x16x32_bf16 v[46:49], v[46:49], v[18:21], v[6:9]
	s_waitcnt lgkmcnt(4)
	v_mfma_f32_16x16x32_bf16 v[64:67], v[56:59], v[14:17], v[6:9]
	v_mfma_f32_16x16x32_bf16 v[56:59], v[56:59], v[18:21], v[6:9]
	s_waitcnt lgkmcnt(3)
	v_mfma_f32_16x16x32_bf16 v[76:79], v[68:71], v[14:17], v[6:9]
	v_mfma_f32_16x16x32_bf16 v[68:71], v[68:71], v[18:21], v[6:9]
	s_waitcnt lgkmcnt(2)
	v_mfma_f32_16x16x32_bf16 v[80:83], v[72:75], v[14:17], v[6:9]
	v_mfma_f32_16x16x32_bf16 v[72:75], v[72:75], v[18:21], v[6:9]
	s_waitcnt lgkmcnt(1)
	v_mfma_f32_16x16x32_bf16 v[92:95], v[84:87], v[14:17], v[6:9]
	v_mfma_f32_16x16x32_bf16 v[84:87], v[84:87], v[18:21], v[6:9]
	s_waitcnt lgkmcnt(0)
	v_mfma_f32_16x16x32_bf16 v[96:99], v[88:91], v[14:17], v[6:9]
	v_mfma_f32_16x16x32_bf16 v[6:9], v[88:91], v[18:21], v[6:9]
	ds_read_b128 v[88:91], v121 offset:64
	ds_read_b128 v[100:103], v121 offset:3392
	s_waitcnt vmcnt(3) lgkmcnt(1)
; #define LASP __attribute__((address_space(3)))
; template <int DQK>
; __device__ __forceinline__ void flash_item(unsigned char* smem, const bf16_t* Q, int qs, const bf16_t* K0, const bf16_t* V0, int n0, const bf16_t* K1, const bf16_t* V1, int n1, int ks, int vs, bf16_t* Oo, int os, float shift) {
;     ...
;         for (int kk = 0; kk < NKK; ++kk) {
; #pragma unroll
;             for (int kg = 0; kg < NKG; ++kg) {
;                 const bf16x8_t kf = *(const LASP bf16x8_t*)(ls + (kg * 16 + fr) * KR + (kk * 32 + fq * 8) * 2);
;                 s[kg][0] = __builtin_amdgcn_mfma_f32_16x16x32_bf16(kf, qf[0][kk], s[kg][0], 0, 0, 0);
;                 s[kg][1] = __builtin_amdgcn_mfma_f32_16x16x32_bf16(kf, qf[1][kk], s[kg][1], 0, 0, 0);
;             }
;             asm volatile("" ::: "memory");
;         }
;         if (t + 1 < ntiles) FL_LOAD((t + 1) * KT);
; #pragma unroll
;         for (int qg = 0; qg < 2; ++qg) {
;             float ps = 0.f;
; #pragma unroll
;             for (int kg = 0; kg < NKG; ++kg)
; #pragma unroll
;                 for (int j = 0; j < 4; ++j) { const float p = __builtin_amdgcn_exp2f(s[kg][qg][j]); s[kg][qg][j] = p; ps += p; }
;             lsum[qg] += ps;
;         }
; #pragma unroll
;         for (int kp = 0; kp < NKP; ++kp) {
;             bf16x8_t pb[2];
; #pragma unroll
;             for (int qg = 0; qg < 2; ++qg) {
;                 const f32x4_t a = s[2 * kp][qg], b = s[2 * kp + 1][qg];
;                 u32x4_t pk; pk.x = pg8::cvt_pk_bf16(a[0], a[1]); pk.y = pg8::cvt_pk_bf16(a[2], a[3]); pk.z = pg8::cvt_pk_bf16(b[0], b[1]); pk.w = pg8::cvt_pk_bf16(b[2], b[3]);
;                 pb[qg] = __builtin_bit_cast(bf16x8_t, pk);
;             }
; #pragma unroll
;             for (int dg = 0; dg < 4; ++dg) {
;                 LASP unsigned char* va = ls + VOFF + (32 * kp + 4 * fq + (fr >> 2)) * VR + (16 * dg + 4 * (fr & 3)) * 2;
;                 const s16x4 v0 = __builtin_amdgcn_ds_read_tr16_b64_v4i16((LASP s16x4*)va);
;                 const s16x4 v1 = __builtin_amdgcn_ds_read_tr16_b64_v4i16((LASP s16x4*)(va + 16 * VR));
;                 const bf16x8_t vf = __builtin_shufflevector(v0, v1, 0, 1, 2, 3, 4, 5, 6, 7);
;                 o[dg][0] = __builtin_amdgcn_mfma_f32_16x16x32_bf16(vf, pb[0], o[dg][0], 0, 0, 0);
;                 o[dg][1] = __builtin_amdgcn_mfma_f32_16x16x32_bf16(vf, pb[1], o[dg][1], 0, 0, 0);
;             }
	v_mfma_f32_16x16x32_bf16 v[38:41], v[88:91], v[22:25], v[38:41]
	s_waitcnt vmcnt(1)
	v_mfma_f32_16x16x32_bf16 v[2:5], v[88:91], v[30:33], v[2:5]
	s_waitcnt lgkmcnt(0)
	v_mfma_f32_16x16x32_bf16 v[42:45], v[100:103], v[22:25], v[42:45]
	v_mfma_f32_16x16x32_bf16 v[10:13], v[100:103], v[30:33], v[10:13]
	ds_read_b128 v[88:91], v121 offset:6720
	ds_read_b128 v[100:103], v121 offset:10048
	s_waitcnt lgkmcnt(1)
	v_mfma_f32_16x16x32_bf16 v[60:63], v[88:91], v[22:25], v[60:63]
	v_mfma_f32_16x16x32_bf16 v[46:49], v[88:91], v[30:33], v[46:49]
	s_waitcnt lgkmcnt(0)
	v_mfma_f32_16x16x32_bf16 v[64:67], v[100:103], v[22:25], v[64:67]
	v_mfma_f32_16x16x32_bf16 v[56:59], v[100:103], v[30:33], v[56:59]
	ds_read_b128 v[88:91], v121 offset:13376
	ds_read_b128 v[100:103], v121 offset:16704
	s_waitcnt lgkmcnt(1)
	v_mfma_f32_16x16x32_bf16 v[76:79], v[88:91], v[22:25], v[76:79]
	v_mfma_f32_16x16x32_bf16 v[68:71], v[88:91], v[30:33], v[68:71]
	s_waitcnt lgkmcnt(0)
	v_mfma_f32_16x16x32_bf16 v[80:83], v[100:103], v[22:25], v[80:83]
	v_mfma_f32_16x16x32_bf16 v[72:75], v[100:103], v[30:33], v[72:75]
	ds_read_b128 v[88:91], v121 offset:20032
	ds_read_b128 v[100:103], v121 offset:23360
	s_waitcnt lgkmcnt(1)
	v_mfma_f32_16x16x32_bf16 v[92:95], v[88:91], v[22:25], v[92:95]
	v_mfma_f32_16x16x32_bf16 v[84:87], v[88:91], v[30:33], v[84:87]
	s_waitcnt lgkmcnt(0)
	v_mfma_f32_16x16x32_bf16 v[88:91], v[100:103], v[22:25], v[96:99]
	v_mfma_f32_16x16x32_bf16 v[96:99], v[100:103], v[30:33], v[6:9]
	s_nop 2
	ds_read_b128 v[6:9], v121 offset:128
	ds_read_b128 v[100:103], v121 offset:3456
	s_waitcnt vmcnt(0) lgkmcnt(1)
	v_mfma_f32_16x16x32_bf16 v[104:107], v[6:9], v[34:37], v[38:41]
	v_mfma_f32_16x16x32_bf16 v[108:111], v[6:9], v[26:29], v[2:5]
	s_nop 2
	ds_read_b128 v[2:5], v121 offset:6784
	ds_read_b128 v[6:9], v121 offset:10112
	s_waitcnt lgkmcnt(1)
	v_mfma_f32_16x16x32_bf16 v[60:63], v[2:5], v[34:37], v[60:63]
	v_mfma_f32_16x16x32_bf16 v[116:119], v[2:5], v[26:29], v[46:49]
	s_waitcnt lgkmcnt(0)
	v_mfma_f32_16x16x32_bf16 v[64:67], v[6:9], v[34:37], v[64:67]
	v_mfma_f32_16x16x32_bf16 v[56:59], v[6:9], v[26:29], v[56:59]
	ds_read_b128 v[2:5], v121 offset:13440
	ds_read_b128 v[6:9], v121 offset:16768
	v_mfma_f32_16x16x32_bf16 v[112:115], v[100:103], v[34:37], v[42:45]
	s_waitcnt lgkmcnt(1)
	v_mfma_f32_16x16x32_bf16 v[132:135], v[2:5], v[34:37], v[76:79]
	v_mfma_f32_16x16x32_bf16 v[46:49], v[2:5], v[26:29], v[68:71]
	s_nop 4
	v_exp_f32_e32 v79, v115
	s_nop 0
	v_exp_f32_e32 v125, v132
	v_lshl_add_u64 v[76:77], v[52:53], 0, s[14:15]
	s_waitcnt lgkmcnt(0)
	v_mfma_f32_16x16x32_bf16 v[42:45], v[6:9], v[26:29], v[72:75]
	ds_read_b128 v[2:5], v121 offset:20096
	s_nop 1
	ds_read_b128 v[72:75], v121 offset:23424
	v_exp_f32_e32 v124, v46
	v_mfma_f32_16x16x32_bf16 v[100:103], v[100:103], v[26:29], v[10:13]
	v_mfma_f32_16x16x32_bf16 v[68:71], v[6:9], v[34:37], v[80:83]
	s_waitcnt lgkmcnt(1)
	v_mfma_f32_16x16x32_bf16 v[38:41], v[2:5], v[34:37], v[92:95]
	s_nop 0
	v_exp_f32_e32 v83, v113
	v_exp_f32_e32 v81, v114
	s_nop 1
	v_exp_f32_e32 v82, v101
	v_mfma_f32_16x16x32_bf16 v[6:9], v[2:5], v[26:29], v[84:87]
	v_bfe_u32 v2, v126, 2, 2
	v_or_b32_e32 v194, v145, v2
	v_mad_u32_u24 v55, v194, s89, v131
	s_waitcnt lgkmcnt(0)
	v_mfma_f32_16x16x32_bf16 v[10:13], v[72:75], v[34:37], v[88:91]
	v_exp_f32_e32 v93, v104
	v_exp_f32_e32 v87, v107
	v_exp_f32_e32 v85, v112
	v_mfma_f32_16x16x32_bf16 v[2:5], v[72:75], v[26:29], v[96:99]
	v_exp_f32_e32 v91, v105
	v_exp_f32_e32 v89, v106
	v_exp_f32_e32 v92, v108
	v_exp_f32_e32 v90, v109
	v_exp_f32_e32 v88, v110
	v_exp_f32_e32 v86, v111
	v_exp_f32_e32 v84, v100
	v_exp_f32_e32 v80, v102
	v_exp_f32_e32 v78, v103
	ds_read_b64_tr_b16 v[96:97], v55 offset:35072
	ds_read_b64_tr_b16 v[94:95], v55 offset:32768
	ds_read_b64_tr_b16 v[98:99], v55 offset:32800
	ds_read_b64_tr_b16 v[120:121], v55 offset:32832
	ds_read_b64_tr_b16 v[136:137], v55 offset:32864
	ds_read_b64_tr_b16 v[100:101], v55 offset:35104
	ds_read_b64_tr_b16 v[122:123], v55 offset:35136
	ds_read_b64_tr_b16 v[138:139], v55 offset:35168
	v_cvt_pk_bf16_f32 v72, v93, v91
	v_cvt_pk_bf16_f32 v73, v89, v87
	v_cvt_pk_bf16_f32 v74, v85, v83
	v_cvt_pk_bf16_f32 v75, v81, v79
	v_cvt_pk_bf16_f32 v110, v92, v90
	v_cvt_pk_bf16_f32 v111, v88, v86
	v_cvt_pk_bf16_f32 v112, v84, v82
	v_cvt_pk_bf16_f32 v113, v80, v78
	s_waitcnt lgkmcnt(6)
	v_mfma_f32_16x16x32_bf16 v[146:149], v[94:97], v[72:75], 0
	v_exp_f32_e32 v109, v60
	v_exp_f32_e32 v107, v61
	v_exp_f32_e32 v105, v62
	v_mfma_f32_16x16x32_bf16 v[150:153], v[94:97], v[110:113], 0
	v_exp_f32_e32 v103, v63
	v_exp_f32_e32 v97, v66
	v_exp_f32_e32 v95, v67
	s_waitcnt lgkmcnt(2)
	v_mfma_f32_16x16x32_bf16 v[156:159], v[98:101], v[72:75], 0
	v_exp_f32_e32 v108, v116
	v_exp_f32_e32 v106, v117
	v_exp_f32_e32 v104, v118
	v_mfma_f32_16x16x32_bf16 v[60:63], v[98:101], v[110:113], 0
	v_exp_f32_e32 v101, v64
	v_exp_f32_e32 v99, v65
	v_exp_f32_e32 v102, v119
	s_waitcnt lgkmcnt(1)
	v_mfma_f32_16x16x32_bf16 v[64:67], v[120:123], v[110:113], 0
	v_exp_f32_e32 v100, v56
	v_exp_f32_e32 v98, v57
	v_exp_f32_e32 v96, v58
	v_exp_f32_e32 v94, v59
	s_waitcnt lgkmcnt(0)
	v_mfma_f32_16x16x32_bf16 v[56:59], v[136:139], v[110:113], 0
	ds_read_b64_tr_b16 v[110:111], v55 offset:37376
	ds_read_b64_tr_b16 v[112:113], v55 offset:39680
	ds_read_b64_tr_b16 v[114:115], v55 offset:37408
	ds_read_b64_tr_b16 v[168:169], v55 offset:37440
	ds_read_b64_tr_b16 v[172:173], v55 offset:37472
	ds_read_b64_tr_b16 v[116:117], v55 offset:39712
	ds_read_b64_tr_b16 v[170:171], v55 offset:39744
	ds_read_b64_tr_b16 v[174:175], v55 offset:39776
	v_cvt_pk_bf16_f32 v164, v108, v106
	v_mfma_f32_16x16x32_bf16 v[160:163], v[120:123], v[72:75], 0
	v_cvt_pk_bf16_f32 v165, v104, v102
	v_cvt_pk_bf16_f32 v166, v100, v98
	v_cvt_pk_bf16_f32 v167, v96, v94
	v_mfma_f32_16x16x32_bf16 v[72:75], v[136:139], v[72:75], 0
	v_cvt_pk_bf16_f32 v136, v109, v107
	v_cvt_pk_bf16_f32 v137, v105, v103
	v_cvt_pk_bf16_f32 v138, v101, v99
	v_cvt_pk_bf16_f32 v139, v97, v95
	s_waitcnt lgkmcnt(6)
; __device__ __forceinline__ unsigned cvt_pk_bf16(float lo, float hi) { const f32x2c f = {lo, hi}; return __builtin_bit_cast(unsigned, __builtin_convertvector(f, bf16x2c)); }
; #define LASP __attribute__((address_space(3)))
; template <int DQK>
; __device__ __forceinline__ void flash_item(unsigned char* smem, const bf16_t* Q, int qs, const bf16_t* K0, const bf16_t* V0, int n0, const bf16_t* K1, const bf16_t* V1, int n1, int ks, int vs, bf16_t* Oo, int os, float shift) {
;     ...
;         if (t + 1 < ntiles) FL_LOAD((t + 1) * KT);
; #pragma unroll
;         for (int qg = 0; qg < 2; ++qg) {
;             float ps = 0.f;
; #pragma unroll
;             for (int kg = 0; kg < NKG; ++kg)
; #pragma unroll
;                 for (int j = 0; j < 4; ++j) { const float p = __builtin_amdgcn_exp2f(s[kg][qg][j]); s[kg][qg][j] = p; ps += p; }
;             lsum[qg] += ps;
;         }
; #pragma unroll
;         for (int kp = 0; kp < NKP; ++kp) {
;             bf16x8_t pb[2];
; #pragma unroll
;             for (int qg = 0; qg < 2; ++qg) {
;                 const f32x4_t a = s[2 * kp][qg], b = s[2 * kp + 1][qg];
;                 u32x4_t pk; pk.x = pg8::cvt_pk_bf16(a[0], a[1]); pk.y = pg8::cvt_pk_bf16(a[2], a[3]); pk.z = pg8::cvt_pk_bf16(b[0], b[1]); pk.w = pg8::cvt_pk_bf16(b[2], b[3]);
;                 pb[qg] = __builtin_bit_cast(bf16x8_t, pk);
;             }
; #pragma unroll
;             for (int dg = 0; dg < 4; ++dg) {
;                 LASP unsigned char* va = ls + VOFF + (32 * kp + 4 * fq + (fr >> 2)) * VR + (16 * dg + 4 * (fr & 3)) * 2;
;                 const s16x4 v0 = __builtin_amdgcn_ds_read_tr16_b64_v4i16((LASP s16x4*)va);
;                 const s16x4 v1 = __builtin_amdgcn_ds_read_tr16_b64_v4i16((LASP s16x4*)(va + 16 * VR));
;                 const bf16x8_t vf = __builtin_shufflevector(v0, v1, 0, 1, 2, 3, 4, 5, 6, 7);
;                 o[dg][0] = __builtin_amdgcn_mfma_f32_16x16x32_bf16(vf, pb[0], o[dg][0], 0, 0, 0);
;                 o[dg][1] = __builtin_amdgcn_mfma_f32_16x16x32_bf16(vf, pb[1], o[dg][1], 0, 0, 0);
;             }
	v_mfma_f32_16x16x32_bf16 v[150:153], v[110:113], v[164:167], v[150:153]
	v_exp_f32_e32 v123, v133
	v_exp_f32_e32 v121, v134
	v_exp_f32_e32 v119, v135
	v_mfma_f32_16x16x32_bf16 v[146:149], v[110:113], v[136:139], v[146:149]
	v_exp_f32_e32 v113, v70
	v_exp_f32_e32 v111, v71
	v_exp_f32_e32 v122, v47
	s_waitcnt lgkmcnt(2)
	v_mfma_f32_16x16x32_bf16 v[156:159], v[114:117], v[136:139], v[156:159]
	v_exp_f32_e32 v120, v48
	v_exp_f32_e32 v118, v49
	v_exp_f32_e32 v112, v44
	v_mfma_f32_16x16x32_bf16 v[60:63], v[114:117], v[164:167], v[60:63]
	v_exp_f32_e32 v117, v68
	v_exp_f32_e32 v115, v69
	v_exp_f32_e32 v116, v42
	v_exp_f32_e32 v114, v43
	v_exp_f32_e32 v110, v45
	ds_read_b64_tr_b16 v[68:69], v55 offset:41984
	ds_read_b64_tr_b16 v[70:71], v55 offset:44288
	s_waitcnt lgkmcnt(3)
	v_mfma_f32_16x16x32_bf16 v[132:135], v[168:171], v[136:139], v[160:163]
	v_exp_f32_e32 v141, v38
	v_exp_f32_e32 v181, v39
	v_exp_f32_e32 v183, v40
	v_mfma_f32_16x16x32_bf16 v[64:67], v[168:171], v[164:167], v[64:67]
	v_exp_f32_e32 v185, v41
	v_exp_f32_e32 v187, v10
	v_exp_f32_e32 v189, v11
	s_waitcnt lgkmcnt(2)
	v_mfma_f32_16x16x32_bf16 v[46:49], v[172:175], v[136:139], v[72:75]
	v_exp_f32_e32 v191, v12
	v_exp_f32_e32 v193, v13
	v_exp_f32_e32 v140, v6
	v_mfma_f32_16x16x32_bf16 v[42:45], v[172:175], v[164:167], v[56:59]
	ds_read_b64_tr_b16 v[136:137], v55 offset:42016
	ds_read_b64_tr_b16 v[160:161], v55 offset:42048
	ds_read_b64_tr_b16 v[164:165], v55 offset:42080
	ds_read_b64_tr_b16 v[138:139], v55 offset:44320
	ds_read_b64_tr_b16 v[162:163], v55 offset:44352
	ds_read_b64_tr_b16 v[166:167], v55 offset:44384
	v_cvt_pk_bf16_f32 v56, v125, v123
	v_cvt_pk_bf16_f32 v57, v121, v119
	v_cvt_pk_bf16_f32 v58, v117, v115
	v_cvt_pk_bf16_f32 v59, v113, v111
	v_cvt_pk_bf16_f32 v72, v124, v122
	v_cvt_pk_bf16_f32 v73, v120, v118
	v_cvt_pk_bf16_f32 v74, v116, v114
	v_cvt_pk_bf16_f32 v75, v112, v110
	v_exp_f32_e32 v180, v7
	v_exp_f32_e32 v182, v8
	v_exp_f32_e32 v184, v9
	v_exp_f32_e32 v186, v2
	v_exp_f32_e32 v188, v3
	v_exp_f32_e32 v190, v4
	v_exp_f32_e32 v192, v5
	ds_read_b64_tr_b16 v[2:3], v55 offset:46592
	ds_read_b64_tr_b16 v[4:5], v55 offset:48896
	s_waitcnt lgkmcnt(8)
	v_mfma_f32_16x16x32_bf16 v[146:149], v[68:71], v[56:59], v[146:149]
	ds_read_b64_tr_b16 v[6:7], v55 offset:46624
	ds_read_b64_tr_b16 v[172:173], v55 offset:46656
	ds_read_b64_tr_b16 v[176:177], v55 offset:46688
	ds_read_b64_tr_b16 v[8:9], v55 offset:48928
	ds_read_b64_tr_b16 v[174:175], v55 offset:48960
	ds_read_b64_tr_b16 v[178:179], v55 offset:48992
	v_cvt_pk_bf16_f32 v168, v140, v180
	v_cvt_pk_bf16_f32 v169, v182, v184
	v_mfma_f32_16x16x32_bf16 v[68:71], v[68:71], v[72:75], v[150:153]
	v_cvt_pk_bf16_f32 v170, v186, v188
	v_cvt_pk_bf16_f32 v171, v190, v192
	v_pk_add_f32 v[92:93], v[92:93], 0 op_sel_hi:[1,0]
	s_waitcnt lgkmcnt(10)
	v_mfma_f32_16x16x32_bf16 v[150:153], v[136:139], v[56:59], v[156:159]
	v_add_f32_e64 v90, v90, v92
	v_add_f32_e64 v91, v91, v93
	v_pk_add_f32 v[88:89], v[88:89], v[90:91]
	v_mfma_f32_16x16x32_bf16 v[136:139], v[136:139], v[72:75], v[60:63]
	v_add_f32_e64 v86, v86, v88
	v_add_f32_e64 v87, v87, v89
	v_pk_add_f32 v[84:85], v[84:85], v[86:87]
	s_waitcnt lgkmcnt(9)
	v_mfma_f32_16x16x32_bf16 v[132:135], v[160:163], v[56:59], v[132:135]
	v_add_f32_e64 v82, v82, v84
	v_add_f32_e64 v83, v83, v85
	v_pk_add_f32 v[80:81], v[80:81], v[82:83]
	v_mfma_f32_16x16x32_bf16 v[10:13], v[160:163], v[72:75], v[64:67]
	v_add_f32_e64 v78, v78, v80
	v_add_f32_e64 v79, v79, v81
	v_and_b32_e32 v80, 7, v126
	v_pk_add_f32 v[78:79], v[108:109], v[78:79]
	s_waitcnt lgkmcnt(8)
	v_mfma_f32_16x16x32_bf16 v[156:159], v[164:167], v[56:59], v[46:49]
	v_lshl_add_u64 v[56:57], v[50:51], 0, s[36:37]
	global_load_dwordx4 v[38:41], v[76:77], off offset:64
	s_nop 0
	global_load_dwordx4 v[46:49], v[76:77], off offset:128
	v_mad_i64_i32 v[50:51], s[18:19], v129, s87, v[56:57]
	v_mfma_f32_16x16x32_bf16 v[160:163], v[164:167], v[72:75], v[42:45]
	v_cvt_pk_bf16_f32 v164, v141, v181
	v_cvt_pk_bf16_f32 v165, v183, v185
	v_cvt_pk_bf16_f32 v166, v187, v189
	v_cvt_pk_bf16_f32 v167, v191, v193
	v_add_co_u32_e32 v42, vcc, s5, v52
	s_waitcnt lgkmcnt(6)
	v_mfma_f32_16x16x32_bf16 v[62:65], v[2:5], v[164:167], v[146:149]
	v_addc_co_u32_e32 v43, vcc, 0, v53, vcc
	global_load_dwordx4 v[42:45], v[42:43], off
	s_nop 0
	global_load_dwordx4 v[50:53], v[50:51], off
	v_mfma_f32_16x16x32_bf16 v[58:61], v[2:5], v[168:171], v[68:71]
	v_add_f32_e64 v78, v106, v78
	v_add_f32_e64 v79, v107, v79
	s_mul_hi_i32 s5, s2, 0x240000
	v_pk_add_f32 v[78:79], v[104:105], v[78:79]
	s_waitcnt lgkmcnt(2)
	v_mfma_f32_16x16x32_bf16 v[74:77], v[6:9], v[164:167], v[150:153]
	v_add_f32_e64 v78, v102, v78
	v_add_f32_e64 v79, v103, v79
	v_pk_add_f32 v[78:79], v[100:101], v[78:79]
	v_mfma_f32_16x16x32_bf16 v[2:5], v[6:9], v[168:171], v[136:139]
	v_mad_i64_i32 v[6:7], s[18:19], v54, s87, v[56:57]
	global_load_dwordx4 v[54:57], v[6:7], off
	v_pk_add_f32 v[78:79], v[98:99], v[78:79]
	s_waitcnt lgkmcnt(1)
	v_mfma_f32_16x16x32_bf16 v[70:73], v[172:175], v[164:167], v[132:135]
	v_add_f32_e64 v78, v96, v78
	v_add_f32_e64 v79, v97, v79
	v_pk_add_f32 v[78:79], v[94:95], v[78:79]
	s_waitcnt lgkmcnt(0)
; __device__ __forceinline__ unsigned cvt_pk_bf16(float lo, float hi) { const f32x2c f = {lo, hi}; return __builtin_bit_cast(unsigned, __builtin_convertvector(f, bf16x2c)); }
; #define LASP __attribute__((address_space(3)))
; template <int DQK>
; __device__ __forceinline__ void flash_item(unsigned char* smem, const bf16_t* Q, int qs, const bf16_t* K0, const bf16_t* V0, int n0, const bf16_t* K1, const bf16_t* V1, int n1, int ks, int vs, bf16_t* Oo, int os, float shift) {
;     ...
;     for (int t = 0; t < ntiles; ++t) {
;         __syncthreads();
; #pragma unroll
;         for (int c = 0; c < NKC; ++c) *(LASP u32x4_t*)(ls + (tid >> 2) * KR + ((tid & 3) + 4 * c) * 16) = kreg[c];
; #pragma unroll
;         for (int c = 0; c < NVC; ++c) *(LASP u32x4_t*)(ls + VOFF + ((tid >> 3) + 64 * c) * VR + (tid & 7) * 16) = vreg[c];
;         __syncthreads();
;     ...
;         for (int qg = 0; qg < 2; ++qg) {
;             float ps = 0.f;
; #pragma unroll
;             for (int kg = 0; kg < NKG; ++kg)
; #pragma unroll
;                 for (int j = 0; j < 4; ++j) { const float p = __builtin_amdgcn_exp2f(s[kg][qg][j]); s[kg][qg][j] = p; ps += p; }
;             lsum[qg] += ps;
;         }
; #pragma unroll
;         for (int kp = 0; kp < NKP; ++kp) {
;             bf16x8_t pb[2];
; #pragma unroll
;             for (int qg = 0; qg < 2; ++qg) {
;                 const f32x4_t a = s[2 * kp][qg], b = s[2 * kp + 1][qg];
;                 u32x4_t pk; pk.x = pg8::cvt_pk_bf16(a[0], a[1]); pk.y = pg8::cvt_pk_bf16(a[2], a[3]); pk.z = pg8::cvt_pk_bf16(b[0], b[1]); pk.w = pg8::cvt_pk_bf16(b[2], b[3]);
;                 pb[qg] = __builtin_bit_cast(bf16x8_t, pk);
;             }
	v_mfma_f32_16x16x32_bf16 v[66:69], v[176:179], v[164:167], v[156:159]
	v_add_f32_e64 v78, v124, v78
	v_add_f32_e64 v79, v125, v79
	v_mad_i64_i32 v[132:133], s[18:19], v129, s87, 0
	v_pk_add_f32 v[78:79], v[122:123], v[78:79]
	v_mfma_f32_16x16x32_bf16 v[6:9], v[172:175], v[168:171], v[10:13]
	v_add_f32_e64 v78, v120, v78
	v_add_f32_e64 v79, v121, v79
	v_mul_u32_u24_e32 v129, 0xd0, v130
	v_pk_add_f32 v[78:79], v[118:119], v[78:79]
	v_mfma_f32_16x16x32_bf16 v[10:13], v[176:179], v[168:171], v[160:163]
	v_add_f32_e64 v78, v116, v78
	v_add_f32_e64 v79, v117, v79
	v_mul_u32_u24_e32 v130, 0x90, v194
	v_pk_add_f32 v[78:79], v[114:115], v[78:79]
	v_add_u32_e32 v162, v128, v129
	v_pk_add_f32 v[78:79], v[112:113], v[78:79]
	v_add_u32_e32 v163, v131, v130
	v_pk_add_f32 v[78:79], v[110:111], v[78:79]
	s_nop 0
	v_pk_add_f32 v[78:79], v[140:141], v[78:79]
	s_nop 0
	v_pk_add_f32 v[78:79], v[180:181], v[78:79]
	s_nop 0
	v_pk_add_f32 v[78:79], v[182:183], v[78:79]
	s_nop 0
	v_pk_add_f32 v[78:79], v[184:185], v[78:79]
	s_nop 0
	v_pk_add_f32 v[78:79], v[186:187], v[78:79]
	s_nop 0
	v_pk_add_f32 v[78:79], v[188:189], v[78:79]
	s_nop 0
	v_pk_add_f32 v[78:79], v[190:191], v[78:79]
	s_nop 0
	v_pk_add_f32 v[78:79], v[192:193], v[78:79]
	s_nop 0
	v_pk_add_f32 v[156:157], v[78:79], 0 op_sel_hi:[1,0]
	v_mov_b32_e32 v78, 0x180000
	v_mad_i64_i32 v[78:79], s[18:19], s2, v78, v[132:133]
	s_add_u32 s18, s38, 0x19418040
	v_lshl_or_b32 v78, v80, 4, v78
	s_addc_u32 s19, s5, 0
	v_lshl_add_u64 v[158:159], v[78:79], 0, s[20:21]
	v_mov_b64_e32 v[78:79], s[18:19]
	v_mad_i64_i32 v[78:79], s[18:19], v127, s91, v[78:79]
	v_and_b32_e32 v80, 3, v126
	v_lshl_or_b32 v78, v80, 4, v78
	v_lshl_add_u64 v[160:161], v[78:79], 0, s[16:17]
	v_xor_b32_e32 v1, 0x10000, v1
	v_xor_b32_e32 v143, 0x10000, v143
	s_waitcnt vmcnt(2)
	ds_write_b128 v1, v[42:45]
	ds_write_b128 v1, v[38:41] offset:64
	ds_write_b128 v1, v[46:49] offset:128
	s_waitcnt vmcnt(1)
	ds_write_b128 v143, v[50:53] offset:32768
	s_waitcnt vmcnt(0)
	ds_write_b128 v143, v[54:57] offset:41984
	v_xor_b32_e32 v162, 0x10000, v162
	v_xor_b32_e32 v163, 0x10000, v163
	s_waitcnt lgkmcnt(0)
	s_barrier
	s_branch .LBB0_832
.LBB0_831:
	ds_read_b64_tr_b16 v[182:183], v163 offset:35072
	ds_read_b64_tr_b16 v[180:181], v163 offset:32768
	ds_read_b64_tr_b16 v[184:185], v163 offset:32832
	ds_read_b64_tr_b16 v[186:187], v163 offset:35136
	ds_read_b64_tr_b16 v[188:189], v163 offset:32864
	ds_read_b64_tr_b16 v[190:191], v163 offset:35168
	ds_read_b64_tr_b16 v[192:193], v163 offset:32800
	ds_read_b64_tr_b16 v[194:195], v163 offset:35104
	ds_read_b64_tr_b16 v[196:197], v163 offset:37376
	ds_read_b64_tr_b16 v[198:199], v163 offset:39680
	ds_read_b64_tr_b16 v[200:201], v163 offset:37408
	ds_read_b64_tr_b16 v[202:203], v163 offset:39712
	s_nop 0
	v_exp_f32_e32 v148, v138
	v_exp_f32_e32 v149, v139
	v_exp_f32_e32 v150, v140
	v_exp_f32_e32 v151, v141
	v_add_f32_e32 v138, 0, v148
	v_exp_f32_e32 v152, v134
	v_add_f32_e32 v138, v149, v138
	v_exp_f32_e32 v153, v135
	v_add_f32_e32 v138, v150, v138
	v_exp_f32_e32 v166, v136
	v_add_f32_e32 v138, v151, v138
	v_exp_f32_e32 v167, v137
	v_add_f32_e32 v134, v152, v138
	v_exp_f32_e32 v136, v130
	v_add_f32_e32 v134, v153, v134
	v_exp_f32_e32 v137, v131
	v_add_f32_e32 v134, v166, v134
	v_exp_f32_e32 v138, v132
	v_add_f32_e32 v134, v167, v134
	v_exp_f32_e32 v139, v133
	v_add_f32_e32 v130, v136, v134
	v_exp_f32_e32 v140, v126
	v_add_f32_e32 v130, v137, v130
	v_exp_f32_e32 v141, v127
	v_add_f32_e32 v130, v138, v130
	v_exp_f32_e32 v164, v128
	v_add_f32_e32 v130, v139, v130
	v_exp_f32_e32 v165, v129
	v_add_f32_e32 v126, v140, v130
	v_exp_f32_e32 v130, v110
	v_add_f32_e32 v126, v141, v126
	v_exp_f32_e32 v131, v111
	v_add_f32_e32 v126, v164, v126
	v_exp_f32_e32 v132, v112
	v_add_f32_e32 v126, v165, v126
	v_exp_f32_e32 v133, v113
	v_add_f32_e32 v110, v130, v126
	v_exp_f32_e32 v134, v118
	v_add_f32_e32 v110, v131, v110
	v_exp_f32_e32 v135, v119
	v_exp_f32_e32 v102, v102
	v_add_f32_e32 v110, v132, v110
	v_exp_f32_e32 v103, v103
	v_add_f32_e32 v110, v133, v110
	v_exp_f32_e32 v104, v104
	v_add_f32_e32 v110, v134, v110
	v_exp_f32_e32 v105, v105
	v_add_f32_e32 v147, v135, v110
	v_add_f32_e32 v110, 0, v102
	v_exp_f32_e32 v168, v86
	v_add_f32_e32 v110, v103, v110
	v_exp_f32_e32 v169, v87
	v_add_f32_e32 v110, v104, v110
	v_exp_f32_e32 v170, v88
	v_add_f32_e32 v110, v105, v110
	v_exp_f32_e32 v171, v89
	v_add_f32_e32 v86, v168, v110
	v_exp_f32_e32 v172, v78
	v_add_f32_e32 v86, v169, v86
	v_exp_f32_e32 v173, v79
	v_add_f32_e32 v86, v170, v86
	v_exp_f32_e32 v174, v80
	v_add_f32_e32 v86, v171, v86
	v_exp_f32_e32 v175, v81
	v_add_f32_e32 v78, v172, v86
	v_exp_f32_e32 v176, v90
	v_add_f32_e32 v78, v173, v78
	v_exp_f32_e32 v177, v91
	v_add_f32_e32 v78, v174, v78
	v_exp_f32_e32 v178, v92
	v_add_f32_e32 v78, v175, v78
	v_exp_f32_e32 v179, v93
	v_add_f32_e32 v78, v176, v78
	v_exp_f32_e32 v86, v82
	v_add_f32_e32 v78, v177, v78
	v_exp_f32_e32 v87, v83
	v_add_f32_e32 v78, v178, v78
	v_exp_f32_e32 v88, v84
	v_add_f32_e32 v78, v179, v78
	v_exp_f32_e32 v89, v85
	v_add_f32_e32 v78, v86, v78
	v_exp_f32_e32 v90, v98
	v_add_f32_e32 v78, v87, v78
	v_exp_f32_e32 v91, v99
	v_exp_f32_e32 v127, v120
	v_add_f32_e32 v78, v88, v78
	v_exp_f32_e32 v126, v100
	v_exp_f32_e32 v129, v121
	v_add_f32_e32 v78, v89, v78
	v_exp_f32_e32 v128, v101
	v_exp_f32_e32 v111, v114
	v_add_f32_e32 v78, v90, v78
	v_exp_f32_e32 v110, v94
	v_exp_f32_e32 v115, v115
	v_add_f32_e32 v146, v91, v78
	v_exp_f32_e32 v114, v95
	v_exp_f32_e32 v113, v116
	v_exp_f32_e32 v112, v96
	v_pk_add_f32 v[78:79], v[126:127], v[146:147]
	v_exp_f32_e32 v119, v117
	v_exp_f32_e32 v118, v97
	v_pk_add_f32 v[78:79], v[128:129], v[78:79]
	v_exp_f32_e32 v117, v122
	v_exp_f32_e32 v116, v106
	v_pk_add_f32 v[78:79], v[110:111], v[78:79]
	v_exp_f32_e32 v123, v123
	v_exp_f32_e32 v122, v107
	v_pk_add_f32 v[78:79], v[114:115], v[78:79]
	v_exp_f32_e32 v121, v124
	v_exp_f32_e32 v120, v108
	v_pk_add_f32 v[78:79], v[112:113], v[78:79]
	v_exp_f32_e32 v125, v125
	v_exp_f32_e32 v124, v109
	v_pk_add_f32 v[78:79], v[118:119], v[78:79]
	v_pk_add_f32 v[78:79], v[116:117], v[78:79]
	v_cvt_pk_bf16_f32 v82, v148, v149
	v_pk_add_f32 v[78:79], v[122:123], v[78:79]
	v_cvt_pk_bf16_f32 v83, v150, v151
	v_pk_add_f32 v[78:79], v[120:121], v[78:79]
	v_cvt_pk_bf16_f32 v84, v152, v153
	v_pk_add_f32 v[78:79], v[124:125], v[78:79]
	v_cvt_pk_bf16_f32 v85, v166, v167
	v_pk_add_f32 v[156:157], v[156:157], v[78:79]
	v_cvt_pk_bf16_f32 v78, v102, v103
	v_cvt_pk_bf16_f32 v79, v104, v105
	v_cvt_pk_bf16_f32 v80, v168, v169
	v_cvt_pk_bf16_f32 v81, v170, v171
	ds_read_b64_tr_b16 v[204:205], v163 offset:37440
	ds_read_b64_tr_b16 v[206:207], v163 offset:39744
	s_waitcnt lgkmcnt(12)
; __device__ __forceinline__ unsigned cvt_pk_bf16(float lo, float hi) { const f32x2c f = {lo, hi}; return __builtin_bit_cast(unsigned, __builtin_convertvector(f, bf16x2c)); }
; #define LASP __attribute__((address_space(3)))
; template <int DQK>
; __device__ __forceinline__ void flash_item(unsigned char* smem, const bf16_t* Q, int qs, const bf16_t* K0, const bf16_t* V0, int n0, const bf16_t* K1, const bf16_t* V1, int n1, int ks, int vs, bf16_t* Oo, int os, float shift) {
;     ...
;         __syncthreads();
; #pragma unroll
;         for (int c = 0; c < NKC; ++c) *(LASP u32x4_t*)(ls + (tid >> 2) * KR + ((tid & 3) + 4 * c) * 16) = kreg[c];
; #pragma unroll
;         for (int c = 0; c < NVC; ++c) *(LASP u32x4_t*)(ls + VOFF + ((tid >> 3) + 64 * c) * VR + (tid & 7) * 16) = vreg[c];
;         __syncthreads();
;     ...
;         for (int kp = 0; kp < NKP; ++kp) {
;             bf16x8_t pb[2];
; #pragma unroll
;             for (int qg = 0; qg < 2; ++qg) {
;                 const f32x4_t a = s[2 * kp][qg], b = s[2 * kp + 1][qg];
;                 u32x4_t pk; pk.x = pg8::cvt_pk_bf16(a[0], a[1]); pk.y = pg8::cvt_pk_bf16(a[2], a[3]); pk.z = pg8::cvt_pk_bf16(b[0], b[1]); pk.w = pg8::cvt_pk_bf16(b[2], b[3]);
;                 pb[qg] = __builtin_bit_cast(bf16x8_t, pk);
;             }
; #pragma unroll
;             for (int dg = 0; dg < 4; ++dg) {
;                 LASP unsigned char* va = ls + VOFF + (32 * kp + 4 * fq + (fr >> 2)) * VR + (16 * dg + 4 * (fr & 3)) * 2;
;                 const s16x4 v0 = __builtin_amdgcn_ds_read_tr16_b64_v4i16((LASP s16x4*)va);
;                 const s16x4 v1 = __builtin_amdgcn_ds_read_tr16_b64_v4i16((LASP s16x4*)(va + 16 * VR));
;                 const bf16x8_t vf = __builtin_shufflevector(v0, v1, 0, 1, 2, 3, 4, 5, 6, 7);
;                 o[dg][0] = __builtin_amdgcn_mfma_f32_16x16x32_bf16(vf, pb[0], o[dg][0], 0, 0, 0);
;                 o[dg][1] = __builtin_amdgcn_mfma_f32_16x16x32_bf16(vf, pb[1], o[dg][1], 0, 0, 0);
;             }
	v_mfma_f32_16x16x32_bf16 v[62:65], v[180:183], v[82:85], v[62:65]
	v_lshl_add_u64 v[158:159], v[158:159], 0, s[36:37]
	v_lshl_add_u64 v[160:161], v[160:161], 0, s[14:15]
	v_mfma_f32_16x16x32_bf16 v[58:61], v[180:183], v[78:81], v[58:61]
	s_cmp_lg_u32 s27, s29
	ds_read_b64_tr_b16 v[180:181], v163 offset:37472
	ds_read_b64_tr_b16 v[182:183], v163 offset:39776
	s_waitcnt lgkmcnt(12)
	v_mfma_f32_16x16x32_bf16 v[70:73], v[184:187], v[82:85], v[70:73]
	v_mfma_f32_16x16x32_bf16 v[6:9], v[184:187], v[78:81], v[6:9]
	ds_read_b64_tr_b16 v[184:185], v163 offset:41984
	ds_read_b64_tr_b16 v[186:187], v163 offset:44288
	s_waitcnt lgkmcnt(12)
	v_mfma_f32_16x16x32_bf16 v[66:69], v[188:191], v[82:85], v[66:69]
	v_mfma_f32_16x16x32_bf16 v[10:13], v[188:191], v[78:81], v[10:13]
	ds_read_b64_tr_b16 v[188:189], v163 offset:42016
	ds_read_b64_tr_b16 v[190:191], v163 offset:44320
	s_waitcnt lgkmcnt(12)
	v_mfma_f32_16x16x32_bf16 v[74:77], v[192:195], v[82:85], v[74:77]
	v_cvt_pk_bf16_f32 v82, v172, v173
	v_cvt_pk_bf16_f32 v83, v174, v175
	v_cvt_pk_bf16_f32 v84, v176, v177
	v_mfma_f32_16x16x32_bf16 v[2:5], v[192:195], v[78:81], v[2:5]
	v_cvt_pk_bf16_f32 v78, v136, v137
	v_cvt_pk_bf16_f32 v79, v138, v139
	v_cvt_pk_bf16_f32 v80, v140, v141
	v_cvt_pk_bf16_f32 v81, v164, v165
	v_cvt_pk_bf16_f32 v85, v178, v179
	ds_read_b64_tr_b16 v[192:193], v163 offset:42048
	ds_read_b64_tr_b16 v[194:195], v163 offset:44352
	s_waitcnt lgkmcnt(12)
	v_mfma_f32_16x16x32_bf16 v[62:65], v[196:199], v[78:81], v[62:65]
	v_mfma_f32_16x16x32_bf16 v[58:61], v[196:199], v[82:85], v[58:61]
	ds_read_b64_tr_b16 v[196:197], v163 offset:42080
	ds_read_b64_tr_b16 v[198:199], v163 offset:44384
	s_waitcnt lgkmcnt(12)
	v_mfma_f32_16x16x32_bf16 v[74:77], v[200:203], v[78:81], v[74:77]
	v_mfma_f32_16x16x32_bf16 v[2:5], v[200:203], v[82:85], v[2:5]
	ds_read_b64_tr_b16 v[200:201], v163 offset:46592
	ds_read_b64_tr_b16 v[202:203], v163 offset:48896
	s_waitcnt lgkmcnt(12)
	v_mfma_f32_16x16x32_bf16 v[70:73], v[204:207], v[78:81], v[70:73]
	v_mfma_f32_16x16x32_bf16 v[6:9], v[204:207], v[82:85], v[6:9]
	ds_read_b64_tr_b16 v[204:205], v163 offset:46624
	ds_read_b64_tr_b16 v[206:207], v163 offset:48928
	s_waitcnt lgkmcnt(12)
	v_mfma_f32_16x16x32_bf16 v[10:13], v[180:183], v[82:85], v[10:13]
	v_cvt_pk_bf16_f32 v82, v86, v87
	v_cvt_pk_bf16_f32 v83, v88, v89
	v_mfma_f32_16x16x32_bf16 v[66:69], v[180:183], v[78:81], v[66:69]
	v_cvt_pk_bf16_f32 v78, v130, v131
	v_cvt_pk_bf16_f32 v79, v132, v133
	v_cvt_pk_bf16_f32 v80, v134, v135
	v_cvt_pk_bf16_f32 v81, v127, v129
	v_cvt_pk_bf16_f32 v84, v90, v91
	v_cvt_pk_bf16_f32 v85, v126, v128
	ds_read_b64_tr_b16 v[180:181], v163 offset:46656
	ds_read_b64_tr_b16 v[182:183], v163 offset:48960
	s_waitcnt lgkmcnt(12)
	v_mfma_f32_16x16x32_bf16 v[62:65], v[184:187], v[78:81], v[62:65]
	v_mfma_f32_16x16x32_bf16 v[58:61], v[184:187], v[82:85], v[58:61]
	ds_read_b64_tr_b16 v[184:185], v163 offset:46688
	ds_read_b64_tr_b16 v[186:187], v163 offset:48992
	s_waitcnt lgkmcnt(12)
	v_mfma_f32_16x16x32_bf16 v[74:77], v[188:191], v[78:81], v[74:77]
	v_mfma_f32_16x16x32_bf16 v[2:5], v[188:191], v[82:85], v[2:5]
	s_waitcnt lgkmcnt(10)
	v_mfma_f32_16x16x32_bf16 v[70:73], v[192:195], v[78:81], v[70:73]
	v_mfma_f32_16x16x32_bf16 v[6:9], v[192:195], v[82:85], v[6:9]
	s_waitcnt lgkmcnt(8)
	v_mfma_f32_16x16x32_bf16 v[66:69], v[196:199], v[78:81], v[66:69]
	v_cvt_pk_bf16_f32 v78, v111, v115
	v_cvt_pk_bf16_f32 v79, v113, v119
	v_cvt_pk_bf16_f32 v80, v117, v123
	v_mfma_f32_16x16x32_bf16 v[10:13], v[196:199], v[82:85], v[10:13]
	v_cvt_pk_bf16_f32 v81, v121, v125
	v_cvt_pk_bf16_f32 v82, v110, v114
	v_cvt_pk_bf16_f32 v83, v112, v118
	v_cvt_pk_bf16_f32 v84, v116, v122
	v_cvt_pk_bf16_f32 v85, v120, v124
	s_waitcnt lgkmcnt(6)
	v_mfma_f32_16x16x32_bf16 v[62:65], v[200:203], v[78:81], v[62:65]
	v_mfma_f32_16x16x32_bf16 v[58:61], v[200:203], v[82:85], v[58:61]
	s_waitcnt lgkmcnt(4)
	v_mfma_f32_16x16x32_bf16 v[74:77], v[204:207], v[78:81], v[74:77]
	v_mfma_f32_16x16x32_bf16 v[2:5], v[204:207], v[82:85], v[2:5]
	s_waitcnt lgkmcnt(2)
	v_mfma_f32_16x16x32_bf16 v[70:73], v[180:183], v[78:81], v[70:73]
	v_mfma_f32_16x16x32_bf16 v[6:9], v[180:183], v[82:85], v[6:9]
	s_waitcnt lgkmcnt(0)
	v_mfma_f32_16x16x32_bf16 v[66:69], v[184:187], v[78:81], v[66:69]
	v_mfma_f32_16x16x32_bf16 v[10:13], v[184:187], v[82:85], v[10:13]
	s_cbranch_scc0 .LBB0_834
	v_xor_b32_e32 v1, 0x10000, v1
	v_xor_b32_e32 v143, 0x10000, v143
	s_waitcnt vmcnt(2)
	ds_write_b128 v1, v[42:45]
	ds_write_b128 v1, v[38:41] offset:64
	ds_write_b128 v1, v[46:49] offset:128
	s_waitcnt vmcnt(1)
	ds_write_b128 v143, v[50:53] offset:32768
	s_waitcnt vmcnt(0)
	ds_write_b128 v143, v[54:57] offset:41984
	v_xor_b32_e32 v162, 0x10000, v162
	v_xor_b32_e32 v163, 0x10000, v163
	s_waitcnt lgkmcnt(0)
	s_barrier
; #define LASP __attribute__((address_space(3)))
; template <int DQK>
; __device__ __forceinline__ void flash_item(unsigned char* smem, const bf16_t* Q, int qs, const bf16_t* K0, const bf16_t* V0, int n0, const bf16_t* K1, const bf16_t* V1, int n1, int ks, int vs, bf16_t* Oo, int os, float shift) {
;     ...
;         f32x4_t s[NKG][2];
; #pragma unroll
;         for (int kg = 0; kg < NKG; ++kg) { s[kg][0] = (f32x4_t){nsh, nsh, nsh, nsh}; s[kg][1] = (f32x4_t){nsh, nsh, nsh, nsh}; }
; #pragma unroll
;         for (int kk = 0; kk < NKK; ++kk) {
; #pragma unroll
;             for (int kg = 0; kg < NKG; ++kg) {
;                 const bf16x8_t kf = *(const LASP bf16x8_t*)(ls + (kg * 16 + fr) * KR + (kk * 32 + fq * 8) * 2);
;                 s[kg][0] = __builtin_amdgcn_mfma_f32_16x16x32_bf16(kf, qf[0][kk], s[kg][0], 0, 0, 0);
;                 s[kg][1] = __builtin_amdgcn_mfma_f32_16x16x32_bf16(kf, qf[1][kk], s[kg][1], 0, 0, 0);
;             }
;             asm volatile("" ::: "memory");
;         }
;         if (t + 1 < ntiles) FL_LOAD((t + 1) * KT);
.LBB0_832:
	ds_read_b128 v[180:183], v162
	ds_read_b128 v[184:187], v162 offset:3328
	ds_read_b128 v[188:191], v162 offset:6656
	ds_read_b128 v[192:195], v162 offset:9984
	ds_read_b128 v[196:199], v162 offset:13312
	ds_read_b128 v[200:203], v162 offset:16640
	ds_read_b128 v[204:207], v162 offset:19968
	ds_read_b128 v[212:215], v162 offset:23296
	ds_read_b128 v[224:227], v162 offset:64
	ds_read_b128 v[228:231], v162 offset:3392
	v_mov_b64_e32 v[84:85], s[46:47]
	v_mov_b64_e32 v[82:83], s[44:45]
	s_add_i32 s29, s29, 1
	s_cmp_ge_u32 s29, s27
	ds_read_b128 v[232:235], v162 offset:6720
	s_waitcnt lgkmcnt(10)
	v_mfma_f32_16x16x32_bf16 v[86:89], v[180:183], v[14:17], v[82:85]
	v_mfma_f32_16x16x32_bf16 v[78:81], v[180:183], v[18:21], v[82:85]
	ds_read_b128 v[180:183], v162 offset:10048
	s_waitcnt lgkmcnt(10)
	v_mfma_f32_16x16x32_bf16 v[94:97], v[184:187], v[14:17], v[82:85]
	v_mfma_f32_16x16x32_bf16 v[90:93], v[184:187], v[18:21], v[82:85]
	ds_read_b128 v[184:187], v162 offset:13376
	s_waitcnt lgkmcnt(10)
	v_mfma_f32_16x16x32_bf16 v[102:105], v[188:191], v[14:17], v[82:85]
	v_mfma_f32_16x16x32_bf16 v[98:101], v[188:191], v[18:21], v[82:85]
	ds_read_b128 v[188:191], v162 offset:16704
	s_waitcnt lgkmcnt(10)
	v_mfma_f32_16x16x32_bf16 v[110:113], v[192:195], v[14:17], v[82:85]
	v_mfma_f32_16x16x32_bf16 v[106:109], v[192:195], v[18:21], v[82:85]
	ds_read_b128 v[192:195], v162 offset:20032
	s_waitcnt lgkmcnt(10)
	v_mfma_f32_16x16x32_bf16 v[118:121], v[196:199], v[14:17], v[82:85]
	v_mfma_f32_16x16x32_bf16 v[114:117], v[196:199], v[18:21], v[82:85]
	ds_read_b128 v[196:199], v162 offset:23360
	s_waitcnt lgkmcnt(10)
	v_mfma_f32_16x16x32_bf16 v[126:129], v[200:203], v[14:17], v[82:85]
	v_mfma_f32_16x16x32_bf16 v[122:125], v[200:203], v[18:21], v[82:85]
	ds_read_b128 v[200:203], v162 offset:128
	s_waitcnt lgkmcnt(10)
	v_mfma_f32_16x16x32_bf16 v[134:137], v[204:207], v[14:17], v[82:85]
	v_mfma_f32_16x16x32_bf16 v[130:133], v[204:207], v[18:21], v[82:85]
	ds_read_b128 v[204:207], v162 offset:3456
	s_waitcnt lgkmcnt(10)
	v_mfma_f32_16x16x32_bf16 v[146:149], v[212:215], v[14:17], v[82:85]
	v_mfma_f32_16x16x32_bf16 v[82:85], v[212:215], v[18:21], v[82:85]
	ds_read_b128 v[212:215], v162 offset:10112
	s_waitcnt lgkmcnt(10)
	v_mfma_f32_16x16x32_bf16 v[86:89], v[224:227], v[22:25], v[86:89]
	v_mfma_f32_16x16x32_bf16 v[78:81], v[224:227], v[30:33], v[78:81]
	ds_read_b128 v[224:227], v162 offset:6784
	s_waitcnt lgkmcnt(10)
	v_mfma_f32_16x16x32_bf16 v[94:97], v[228:231], v[22:25], v[94:97]
	v_mfma_f32_16x16x32_bf16 v[90:93], v[228:231], v[30:33], v[90:93]
	ds_read_b128 v[228:231], v162 offset:13440
	s_waitcnt lgkmcnt(10)
	v_mfma_f32_16x16x32_bf16 v[150:153], v[232:235], v[22:25], v[102:105]
	s_nop 2
	ds_read_b128 v[236:239], v162 offset:16768
	s_waitcnt lgkmcnt(10)
	v_mfma_f32_16x16x32_bf16 v[110:113], v[180:183], v[22:25], v[110:113]
	v_mfma_f32_16x16x32_bf16 v[106:109], v[180:183], v[30:33], v[106:109]
	ds_read_b128 v[180:183], v162 offset:20096
	s_waitcnt lgkmcnt(10)
	v_mfma_f32_16x16x32_bf16 v[118:121], v[184:187], v[22:25], v[118:121]
	v_mfma_f32_16x16x32_bf16 v[114:117], v[184:187], v[30:33], v[114:117]
	ds_read_b128 v[184:187], v162 offset:23424
	s_waitcnt lgkmcnt(10)
	v_mfma_f32_16x16x32_bf16 v[164:167], v[188:191], v[22:25], v[126:129]
	v_mfma_f32_16x16x32_bf16 v[122:125], v[188:191], v[30:33], v[122:125]
	s_waitcnt lgkmcnt(9)
	v_mfma_f32_16x16x32_bf16 v[168:171], v[192:195], v[22:25], v[134:137]
	v_mfma_f32_16x16x32_bf16 v[172:175], v[192:195], v[30:33], v[130:133]
	s_waitcnt lgkmcnt(8)
	v_mfma_f32_16x16x32_bf16 v[176:179], v[196:199], v[30:33], v[82:85]
	s_nop 2
	v_mfma_f32_16x16x32_bf16 v[98:101], v[232:235], v[30:33], v[98:101]
	v_mfma_f32_16x16x32_bf16 v[146:149], v[196:199], v[22:25], v[146:149]
	s_waitcnt lgkmcnt(7)
	v_mfma_f32_16x16x32_bf16 v[138:141], v[200:203], v[34:37], v[86:89]
	v_mfma_f32_16x16x32_bf16 v[102:105], v[200:203], v[26:29], v[78:81]
	s_nop 1
	s_waitcnt lgkmcnt(6)
	v_mfma_f32_16x16x32_bf16 v[134:137], v[204:207], v[34:37], v[94:97]
	s_nop 2
	v_mfma_f32_16x16x32_bf16 v[86:89], v[204:207], v[26:29], v[90:93]
	s_waitcnt lgkmcnt(5)
	v_mfma_f32_16x16x32_bf16 v[126:129], v[212:215], v[34:37], v[110:113]
	v_mfma_f32_16x16x32_bf16 v[90:93], v[212:215], v[26:29], v[106:109]
	s_waitcnt lgkmcnt(4)
	v_mfma_f32_16x16x32_bf16 v[130:133], v[224:227], v[34:37], v[150:153]
	v_mfma_f32_16x16x32_bf16 v[78:81], v[224:227], v[26:29], v[98:101]
	s_waitcnt lgkmcnt(3)
	v_mfma_f32_16x16x32_bf16 v[110:113], v[228:231], v[34:37], v[118:121]
	s_waitcnt lgkmcnt(2)
	v_mfma_f32_16x16x32_bf16 v[118:121], v[236:239], v[34:37], v[164:167]
	v_mfma_f32_16x16x32_bf16 v[98:101], v[236:239], v[26:29], v[122:125]
	v_mfma_f32_16x16x32_bf16 v[82:85], v[228:231], v[26:29], v[114:117]
	s_waitcnt lgkmcnt(1)
	v_mfma_f32_16x16x32_bf16 v[114:117], v[180:183], v[34:37], v[168:171]
	v_mfma_f32_16x16x32_bf16 v[94:97], v[180:183], v[26:29], v[172:175]
	s_waitcnt lgkmcnt(0)
	v_mfma_f32_16x16x32_bf16 v[122:125], v[184:187], v[34:37], v[146:149]
	v_mfma_f32_16x16x32_bf16 v[106:109], v[184:187], v[26:29], v[176:179]
	s_cbranch_scc1 .LBB0_831
	v_lshl_add_u64 v[54:55], s[56:57], 0, v[158:159]
	v_add_co_u32_e32 v50, vcc, 0x1bc98000, v54
	v_lshl_add_u64 v[46:47], s[56:57], 0, v[160:161]
	s_nop 0
	v_addc_co_u32_e32 v51, vcc, 0, v55, vcc
	v_add_co_u32_e32 v54, vcc, 0x1bca4000, v54
	global_load_dwordx4 v[42:45], v[46:47], off offset:-64
	global_load_dwordx4 v[38:41], v[46:47], off
	v_addc_co_u32_e32 v55, vcc, 0, v55, vcc
	global_load_dwordx4 v[46:49], v[46:47], off offset:64
	s_nop 0
	global_load_dwordx4 v[50:53], v[50:51], off
	s_nop 0
	global_load_dwordx4 v[54:57], v[54:55], off
	s_branch .LBB0_831

;     __device__ __forceinline__ void operator()(const f32x4 (&acc)[2][2][4][2], const Unit& u, int wr, int wc, int fr, int fq) const {
;     ...
;         const bool isctx = u.pm >= 128;
;         const float* inb = isctx ? in_ctx : in_lat; float* outb = isctx ? out_ctx : out_lat;
;         const int pml = isctx ? u.pm - 128 : u.pm;
;         const float* gp = gate + (size_t)(isctx ? 16 : (u.pm >> 3)) * 6144;
;         const int row0 = pml * BM + wr * 64 + fr, col0 = u.pn * BM + wc * 32 + 4 * fq;
;         f32x4 gv[2][2];
; #pragma unroll
;         for (int bj = 0; bj < 2; ++bj)
; #pragma unroll
;             for (int n = 0; n < 2; ++n) gv[bj][n] = *(const f32x4*)(gp + col0 + bj * HALF + n * 16);
; #pragma unroll
;         for (int ai = 0; ai < 2; ++ai)
; #pragma unroll
;             for (int m = 0; m < 4; ++m) { const size_t ro = (size_t)(row0 + ai * HALF + m * 16) * 1024 + col0;
; #pragma unroll
;                 for (int bj = 0; bj < 2; ++bj)
; #pragma unroll
;                     for (int n = 0; n < 2; ++n) { const f32x4 x = *(const f32x4*)(inb + ro + bj * HALF + n * 16);
;                         *(f32x4*)(outb + ro + bj * HALF + n * 16) = x + gv[bj][n] * acc[ai][bj][m][n]; } }
.LBB0_979:
	s_and_b64 s[2:3], exec, s[26:27]
	v_readlane_b32 s2, v255, 39
	v_readlane_b32 s16, v255, 41
	v_readlane_b32 s3, v255, 40
	v_readlane_b32 s17, v255, 42
	s_cselect_b32 s3, s3, s17
	s_cselect_b32 s2, s2, s16
	s_cselect_b32 s17, s65, s43
	s_cselect_b32 s16, s64, s42
	s_lshl_b64 s[18:19], s[28:29], 2
	s_add_u32 s18, s52, s18
	s_addc_u32 s19, s53, s19
	s_lshl_b32 s5, s20, 8
	s_add_i32 s21, s5, 0xffff8000
	s_and_b64 s[26:27], exec, s[26:27]
	s_cselect_b32 s5, s21, s5
	v_add_u32_e32 v174, s5, v160
	v_lshl_or_b32 v172, s11, 8, v161
	v_ashrrev_i32_e32 v175, 31, v174
	v_ashrrev_i32_e32 v173, 31, v172
	v_lshlrev_b64 v[146:147], 10, v[174:175]
	v_lshl_add_u64 v[146:147], v[146:147], 0, v[172:173]
	v_lshlrev_b64 v[170:171], 2, v[146:147]
	v_lshl_add_u64 v[130:131], v[172:173], 2, s[18:19]
	v_lshl_add_u64 v[150:151], s[2:3], 0, v[170:171]
	global_load_dwordx4 v[142:145], v[130:131], off
	global_load_dwordx4 v[138:141], v[130:131], off offset:64
	global_load_dwordx4 v[134:137], v[130:131], off offset:512
	s_nop 0
	global_load_dwordx4 v[130:133], v[130:131], off offset:576
	v_lshl_add_u64 v[152:153], s[16:17], 0, v[170:171]
	s_mov_b64 s[98:99], 0x10000
	v_lshl_add_u64 v[176:177], v[150:151], 0, s[98:99]
	v_lshl_add_u64 v[178:179], v[152:153], 0, s[98:99]
	s_mov_b64 s[98:99], 0x20000
	v_lshl_add_u64 v[180:181], v[150:151], 0, s[98:99]
	v_lshl_add_u64 v[182:183], v[152:153], 0, s[98:99]
	s_mov_b64 s[98:99], 0x30000
	v_lshl_add_u64 v[184:185], v[150:151], 0, s[98:99]
	v_lshl_add_u64 v[186:187], v[152:153], 0, s[98:99]
	s_mov_b64 s[98:99], 0x80000
	v_lshl_add_u64 v[188:189], v[150:151], 0, s[98:99]
	v_lshl_add_u64 v[190:191], v[152:153], 0, s[98:99]
	s_mov_b64 s[98:99], 0x90000
	v_lshl_add_u64 v[192:193], v[150:151], 0, s[98:99]
	v_lshl_add_u64 v[194:195], v[152:153], 0, s[98:99]
	s_mov_b64 s[98:99], 0xa0000
	v_lshl_add_u64 v[196:197], v[150:151], 0, s[98:99]
	v_lshl_add_u64 v[198:199], v[152:153], 0, s[98:99]
	s_mov_b64 s[98:99], 0xb0000
	v_lshl_add_u64 v[200:201], v[150:151], 0, s[98:99]
	v_lshl_add_u64 v[202:203], v[152:153], 0, s[98:99]
	global_load_dwordx4 v[204:207], v[150:151], off
	global_load_dwordx4 v[212:215], v[150:151], off offset:64
	global_load_dwordx4 v[224:227], v[150:151], off offset:512
	global_load_dwordx4 v[228:231], v[150:151], off offset:576
	global_load_dwordx4 v[232:235], v[176:177], off
	global_load_dwordx4 v[236:239], v[176:177], off offset:64
	global_load_dwordx4 v[240:243], v[176:177], off offset:512
	global_load_dwordx4 v[244:247], v[176:177], off offset:576
	s_waitcnt vmcnt(7)
	v_pk_fma_f32 v[206:207], v[128:129], v[144:145], v[206:207]
	v_pk_fma_f32 v[204:205], v[126:127], v[142:143], v[204:205]
	global_store_dwordx4 v[152:153], v[204:207], off
	global_load_dwordx4 v[248:251], v[180:181], off
	s_waitcnt vmcnt(8)
	v_pk_fma_f32 v[214:215], v[124:125], v[140:141], v[214:215]
	v_pk_fma_f32 v[212:213], v[122:123], v[138:139], v[212:213]
	global_store_dwordx4 v[152:153], v[212:215], off offset:64
	global_load_dwordx4 v[204:207], v[180:181], off offset:64
	s_waitcnt vmcnt(9)
	v_pk_fma_f32 v[226:227], v[112:113], v[136:137], v[226:227]
	v_pk_fma_f32 v[224:225], v[110:111], v[134:135], v[224:225]
	global_store_dwordx4 v[152:153], v[224:227], off offset:512
	global_load_dwordx4 v[212:215], v[180:181], off offset:512
	s_waitcnt vmcnt(10)
	v_pk_fma_f32 v[230:231], v[104:105], v[132:133], v[230:231]
	v_pk_fma_f32 v[228:229], v[102:103], v[130:131], v[228:229]
	global_store_dwordx4 v[152:153], v[228:231], off offset:576
	global_load_dwordx4 v[224:227], v[180:181], off offset:576
	s_waitcnt vmcnt(11)
	v_pk_fma_f32 v[234:235], v[120:121], v[144:145], v[234:235]
	v_pk_fma_f32 v[232:233], v[118:119], v[142:143], v[232:233]
	global_store_dwordx4 v[178:179], v[232:235], off
	global_load_dwordx4 v[228:231], v[184:185], off
	s_waitcnt vmcnt(12)
	v_pk_fma_f32 v[238:239], v[116:117], v[140:141], v[238:239]
	v_pk_fma_f32 v[236:237], v[114:115], v[138:139], v[236:237]
	global_store_dwordx4 v[178:179], v[236:239], off offset:64
	global_load_dwordx4 v[232:235], v[184:185], off offset:64
	s_waitcnt vmcnt(13)
	v_pk_fma_f32 v[242:243], v[96:97], v[136:137], v[242:243]
	v_pk_fma_f32 v[240:241], v[94:95], v[134:135], v[240:241]
	global_store_dwordx4 v[178:179], v[240:243], off offset:512
	global_load_dwordx4 v[236:239], v[184:185], off offset:512
	s_waitcnt vmcnt(14)
	v_pk_fma_f32 v[246:247], v[88:89], v[132:133], v[246:247]
	v_pk_fma_f32 v[244:245], v[86:87], v[130:131], v[244:245]
	global_store_dwordx4 v[178:179], v[244:247], off offset:576
	global_load_dwordx4 v[240:243], v[184:185], off offset:576
	s_waitcnt vmcnt(14)
	v_pk_fma_f32 v[250:251], v[108:109], v[144:145], v[250:251]
	v_pk_fma_f32 v[248:249], v[106:107], v[142:143], v[248:249]
	global_store_dwordx4 v[182:183], v[248:251], off
	global_load_dwordx4 v[244:247], v[188:189], off
	s_waitcnt vmcnt(14)
	v_pk_fma_f32 v[206:207], v[100:101], v[140:141], v[206:207]
	v_pk_fma_f32 v[204:205], v[98:99], v[138:139], v[204:205]
	global_store_dwordx4 v[182:183], v[204:207], off offset:64
	global_load_dwordx4 v[248:251], v[188:189], off offset:64
	s_waitcnt vmcnt(14)
;     __device__ __forceinline__ void operator()(const f32x4 (&acc)[2][2][4][2], const Unit& u, int wr, int wc, int fr, int fq) const {
;     ...
;             for (int m = 0; m < 4; ++m) { const size_t ro = (size_t)(row0 + ai * HALF + m * 16) * 1024 + col0;
; #pragma unroll
;                 for (int bj = 0; bj < 2; ++bj)
; #pragma unroll
;                     for (int n = 0; n < 2; ++n) { const f32x4 x = *(const f32x4*)(inb + ro + bj * HALF + n * 16);
;                         *(f32x4*)(outb + ro + bj * HALF + n * 16) = x + gv[bj][n] * acc[ai][bj][m][n]; } }
	v_pk_fma_f32 v[214:215], v[80:81], v[136:137], v[214:215]
	v_pk_fma_f32 v[212:213], v[78:79], v[134:135], v[212:213]
	global_store_dwordx4 v[182:183], v[212:215], off offset:512
	global_load_dwordx4 v[204:207], v[188:189], off offset:512
	s_waitcnt vmcnt(14)
	v_pk_fma_f32 v[226:227], v[76:77], v[132:133], v[226:227]
	v_pk_fma_f32 v[224:225], v[74:75], v[130:131], v[224:225]
	global_store_dwordx4 v[182:183], v[224:227], off offset:576
	global_load_dwordx4 v[212:215], v[188:189], off offset:576
	s_waitcnt vmcnt(14)
	v_pk_fma_f32 v[230:231], v[92:93], v[144:145], v[230:231]
	v_pk_fma_f32 v[228:229], v[90:91], v[142:143], v[228:229]
	global_store_dwordx4 v[186:187], v[228:231], off
	global_load_dwordx4 v[224:227], v[192:193], off
	s_waitcnt vmcnt(14)
	v_pk_fma_f32 v[234:235], v[84:85], v[140:141], v[234:235]
	v_pk_fma_f32 v[232:233], v[82:83], v[138:139], v[232:233]
	global_store_dwordx4 v[186:187], v[232:235], off offset:64
	global_load_dwordx4 v[228:231], v[192:193], off offset:64
	s_waitcnt vmcnt(14)
	v_pk_fma_f32 v[238:239], v[72:73], v[136:137], v[238:239]
	v_pk_fma_f32 v[236:237], v[70:71], v[134:135], v[236:237]
	global_store_dwordx4 v[186:187], v[236:239], off offset:512
	global_load_dwordx4 v[232:235], v[192:193], off offset:512
	s_waitcnt vmcnt(14)
	v_pk_fma_f32 v[242:243], v[68:69], v[132:133], v[242:243]
	v_pk_fma_f32 v[240:241], v[66:67], v[130:131], v[240:241]
	global_store_dwordx4 v[186:187], v[240:243], off offset:576
	global_load_dwordx4 v[236:239], v[192:193], off offset:576
	s_waitcnt vmcnt(14)
	v_pk_fma_f32 v[246:247], v[64:65], v[144:145], v[246:247]
	v_pk_fma_f32 v[244:245], v[62:63], v[142:143], v[244:245]
	global_store_dwordx4 v[190:191], v[244:247], off
	global_load_dwordx4 v[240:243], v[196:197], off
	s_waitcnt vmcnt(14)
	v_pk_fma_f32 v[250:251], v[60:61], v[140:141], v[250:251]
	v_pk_fma_f32 v[248:249], v[58:59], v[138:139], v[248:249]
	global_store_dwordx4 v[190:191], v[248:251], off offset:64
	global_load_dwordx4 v[244:247], v[196:197], off offset:64
	s_waitcnt vmcnt(14)
	v_pk_fma_f32 v[206:207], v[48:49], v[136:137], v[206:207]
	v_pk_fma_f32 v[204:205], v[46:47], v[134:135], v[204:205]
	global_store_dwordx4 v[190:191], v[204:207], off offset:512
	global_load_dwordx4 v[248:251], v[196:197], off offset:512
	s_waitcnt vmcnt(14)
	v_pk_fma_f32 v[214:215], v[44:45], v[132:133], v[214:215]
	v_pk_fma_f32 v[212:213], v[42:43], v[130:131], v[212:213]
	global_store_dwordx4 v[190:191], v[212:215], off offset:576
	global_load_dwordx4 v[204:207], v[196:197], off offset:576
	s_waitcnt vmcnt(14)
	v_pk_fma_f32 v[226:227], v[56:57], v[144:145], v[226:227]
	v_pk_fma_f32 v[224:225], v[54:55], v[142:143], v[224:225]
	global_store_dwordx4 v[194:195], v[224:227], off
	global_load_dwordx4 v[212:215], v[200:201], off
	s_waitcnt vmcnt(14)
	v_pk_fma_f32 v[230:231], v[52:53], v[140:141], v[230:231]
	v_pk_fma_f32 v[228:229], v[50:51], v[138:139], v[228:229]
	global_store_dwordx4 v[194:195], v[228:231], off offset:64
	global_load_dwordx4 v[224:227], v[200:201], off offset:64
	s_waitcnt vmcnt(14)
	v_pk_fma_f32 v[234:235], v[32:33], v[136:137], v[234:235]
	v_pk_fma_f32 v[232:233], v[30:31], v[134:135], v[232:233]
	global_store_dwordx4 v[194:195], v[232:235], off offset:512
	global_load_dwordx4 v[228:231], v[200:201], off offset:512
	s_waitcnt vmcnt(14)
	v_pk_fma_f32 v[238:239], v[28:29], v[132:133], v[238:239]
	v_pk_fma_f32 v[236:237], v[26:27], v[130:131], v[236:237]
	global_store_dwordx4 v[194:195], v[236:239], off offset:576
	global_load_dwordx4 v[232:235], v[200:201], off offset:576
	s_waitcnt vmcnt(14)
	v_pk_fma_f32 v[242:243], v[40:41], v[144:145], v[242:243]
	v_pk_fma_f32 v[240:241], v[38:39], v[142:143], v[240:241]
	global_store_dwordx4 v[198:199], v[240:243], off
	s_waitcnt vmcnt(13)
	v_pk_fma_f32 v[246:247], v[36:37], v[140:141], v[246:247]
	v_pk_fma_f32 v[244:245], v[34:35], v[138:139], v[244:245]
	global_store_dwordx4 v[198:199], v[244:247], off offset:64
	s_waitcnt vmcnt(12)
	v_pk_fma_f32 v[250:251], v[16:17], v[136:137], v[250:251]
	v_pk_fma_f32 v[248:249], v[14:15], v[134:135], v[248:249]
	global_store_dwordx4 v[198:199], v[248:251], off offset:512
	s_waitcnt vmcnt(11)
	v_pk_fma_f32 v[206:207], v[12:13], v[132:133], v[206:207]
	v_pk_fma_f32 v[204:205], v[10:11], v[130:131], v[204:205]
	global_store_dwordx4 v[198:199], v[204:207], off offset:576
	s_waitcnt vmcnt(10)
	v_pk_fma_f32 v[214:215], v[24:25], v[144:145], v[214:215]
	v_pk_fma_f32 v[212:213], v[22:23], v[142:143], v[212:213]
	global_store_dwordx4 v[202:203], v[212:215], off
	s_waitcnt vmcnt(9)
	v_pk_fma_f32 v[226:227], v[20:21], v[140:141], v[226:227]
	v_pk_fma_f32 v[224:225], v[18:19], v[138:139], v[224:225]
	global_store_dwordx4 v[202:203], v[224:227], off offset:64
	s_waitcnt vmcnt(8)
	v_pk_fma_f32 v[230:231], v[8:9], v[136:137], v[230:231]
	v_pk_fma_f32 v[228:229], v[6:7], v[134:135], v[228:229]
	global_store_dwordx4 v[202:203], v[228:231], off offset:512
	s_waitcnt vmcnt(7)
	v_pk_fma_f32 v[234:235], v[4:5], v[132:133], v[234:235]
	v_pk_fma_f32 v[232:233], v[2:3], v[130:131], v[232:233]
	global_store_dwordx4 v[202:203], v[232:235], off offset:576
	s_mov_b64 s[2:3], 0

;     __device__ __forceinline__ void operator()(const f32x4 (&acc)[2][2][4][2], const Unit& u, int wr, int wc, int fr, int fq) const {
;     ...
;         const bool isctx = u.pm >= 128;
;         const float* inb = isctx ? in_ctx : in_lat; float* outb = isctx ? out_ctx : out_lat;
;         const int pml = isctx ? u.pm - 128 : u.pm;
;         const float* gp = gate + (size_t)(isctx ? 16 : (u.pm >> 3)) * 6144;
;         const int row0 = pml * BM + wr * 64 + fr, col0 = u.pn * BM + wc * 32 + 4 * fq;
;         f32x4 gv[2][2];
; #pragma unroll
;         for (int bj = 0; bj < 2; ++bj)
; #pragma unroll
;             for (int n = 0; n < 2; ++n) gv[bj][n] = *(const f32x4*)(gp + col0 + bj * HALF + n * 16);
; #pragma unroll
;         for (int ai = 0; ai < 2; ++ai)
; #pragma unroll
;             for (int m = 0; m < 4; ++m) { const size_t ro = (size_t)(row0 + ai * HALF + m * 16) * 1024 + col0;
; #pragma unroll
;                 for (int bj = 0; bj < 2; ++bj)
; #pragma unroll
;                     for (int n = 0; n < 2; ++n) { const f32x4 x = *(const f32x4*)(inb + ro + bj * HALF + n * 16);
;                         *(f32x4*)(outb + ro + bj * HALF + n * 16) = x + gv[bj][n] * acc[ai][bj][m][n]; } }
.LBB0_1199:
	s_and_b64 s[2:3], exec, s[16:17]
	s_cselect_b32 s3, s65, s43
	s_cselect_b32 s2, s64, s42
	s_lshl_b64 s[26:27], s[26:27], 2
	s_add_u32 s26, s50, s26
	s_addc_u32 s27, s51, s27
	s_lshl_b32 s5, s18, 8
	s_add_i32 s19, s5, 0xffff8000
	s_and_b64 s[16:17], exec, s[16:17]
	s_cselect_b32 s5, s19, s5
	v_add_u32_e32 v174, s5, v160
	v_lshl_or_b32 v130, s11, 8, v161
	v_ashrrev_i32_e32 v175, 31, v174
	v_ashrrev_i32_e32 v131, 31, v130
	v_lshlrev_b64 v[146:147], 12, v[174:175]
	v_lshlrev_b64 v[172:173], 2, v[130:131]
	v_lshl_add_u64 v[146:147], s[2:3], 0, v[146:147]
	v_lshl_add_u64 v[130:131], s[26:27], 0, v[172:173]
	v_lshl_add_u64 v[170:171], v[146:147], 0, v[172:173]
	global_load_dwordx4 v[142:145], v[130:131], off
	global_load_dwordx4 v[138:141], v[130:131], off offset:64
	global_load_dwordx4 v[134:137], v[130:131], off offset:512
	s_nop 0
	global_load_dwordx4 v[130:133], v[130:131], off offset:576
	s_nop 0
	s_mov_b64 s[98:99], 0x10000
	v_lshl_add_u64 v[176:177], v[170:171], 0, s[98:99]
	s_mov_b64 s[98:99], 0x20000
	v_lshl_add_u64 v[178:179], v[170:171], 0, s[98:99]
	s_mov_b64 s[98:99], 0x30000
	v_lshl_add_u64 v[180:181], v[170:171], 0, s[98:99]
	s_mov_b64 s[98:99], 0x80000
	v_lshl_add_u64 v[182:183], v[170:171], 0, s[98:99]
	s_mov_b64 s[98:99], 0x90000
	v_lshl_add_u64 v[184:185], v[170:171], 0, s[98:99]
	s_mov_b64 s[98:99], 0xa0000
	v_lshl_add_u64 v[186:187], v[170:171], 0, s[98:99]
	s_mov_b64 s[98:99], 0xb0000
	v_lshl_add_u64 v[188:189], v[170:171], 0, s[98:99]
	global_load_dwordx4 v[204:207], v[170:171], off
	global_load_dwordx4 v[212:215], v[170:171], off offset:64
	global_load_dwordx4 v[224:227], v[170:171], off offset:512
	global_load_dwordx4 v[228:231], v[170:171], off offset:576
	global_load_dwordx4 v[232:235], v[176:177], off
	global_load_dwordx4 v[236:239], v[176:177], off offset:64
	global_load_dwordx4 v[240:243], v[176:177], off offset:512
	global_load_dwordx4 v[244:247], v[176:177], off offset:576
	s_waitcnt vmcnt(7)
	v_pk_fma_f32 v[206:207], v[128:129], v[144:145], v[206:207]
	v_pk_fma_f32 v[204:205], v[126:127], v[142:143], v[204:205]
	global_store_dwordx4 v[170:171], v[204:207], off
	global_load_dwordx4 v[248:251], v[178:179], off
	s_waitcnt vmcnt(8)
	v_pk_fma_f32 v[214:215], v[124:125], v[140:141], v[214:215]
	v_pk_fma_f32 v[212:213], v[122:123], v[138:139], v[212:213]
	global_store_dwordx4 v[170:171], v[212:215], off offset:64
	global_load_dwordx4 v[204:207], v[178:179], off offset:64
	s_waitcnt vmcnt(9)
	v_pk_fma_f32 v[226:227], v[112:113], v[136:137], v[226:227]
	v_pk_fma_f32 v[224:225], v[110:111], v[134:135], v[224:225]
	global_store_dwordx4 v[170:171], v[224:227], off offset:512
	global_load_dwordx4 v[212:215], v[178:179], off offset:512
	s_waitcnt vmcnt(10)
	v_pk_fma_f32 v[230:231], v[104:105], v[132:133], v[230:231]
	v_pk_fma_f32 v[228:229], v[102:103], v[130:131], v[228:229]
	global_store_dwordx4 v[170:171], v[228:231], off offset:576
	global_load_dwordx4 v[224:227], v[178:179], off offset:576
	s_waitcnt vmcnt(11)
	v_pk_fma_f32 v[234:235], v[120:121], v[144:145], v[234:235]
	v_pk_fma_f32 v[232:233], v[118:119], v[142:143], v[232:233]
	global_store_dwordx4 v[176:177], v[232:235], off
	global_load_dwordx4 v[228:231], v[180:181], off
	s_waitcnt vmcnt(12)
	v_pk_fma_f32 v[238:239], v[116:117], v[140:141], v[238:239]
	v_pk_fma_f32 v[236:237], v[114:115], v[138:139], v[236:237]
	global_store_dwordx4 v[176:177], v[236:239], off offset:64
	global_load_dwordx4 v[232:235], v[180:181], off offset:64
	s_waitcnt vmcnt(13)
	v_pk_fma_f32 v[242:243], v[96:97], v[136:137], v[242:243]
	v_pk_fma_f32 v[240:241], v[94:95], v[134:135], v[240:241]
	global_store_dwordx4 v[176:177], v[240:243], off offset:512
	global_load_dwordx4 v[236:239], v[180:181], off offset:512
	s_waitcnt vmcnt(14)
	v_pk_fma_f32 v[246:247], v[88:89], v[132:133], v[246:247]
	v_pk_fma_f32 v[244:245], v[86:87], v[130:131], v[244:245]
	global_store_dwordx4 v[176:177], v[244:247], off offset:576
	global_load_dwordx4 v[240:243], v[180:181], off offset:576
	s_waitcnt vmcnt(14)
	v_pk_fma_f32 v[250:251], v[108:109], v[144:145], v[250:251]
	v_pk_fma_f32 v[248:249], v[106:107], v[142:143], v[248:249]
	global_store_dwordx4 v[178:179], v[248:251], off
	global_load_dwordx4 v[244:247], v[182:183], off
	s_waitcnt vmcnt(14)
	v_pk_fma_f32 v[206:207], v[100:101], v[140:141], v[206:207]
	v_pk_fma_f32 v[204:205], v[98:99], v[138:139], v[204:205]
	global_store_dwordx4 v[178:179], v[204:207], off offset:64
	global_load_dwordx4 v[248:251], v[182:183], off offset:64
	s_waitcnt vmcnt(14)
	v_pk_fma_f32 v[214:215], v[80:81], v[136:137], v[214:215]
	v_pk_fma_f32 v[212:213], v[78:79], v[134:135], v[212:213]
	global_store_dwordx4 v[178:179], v[212:215], off offset:512
	global_load_dwordx4 v[204:207], v[182:183], off offset:512
	s_waitcnt vmcnt(14)
;     __device__ __forceinline__ void operator()(const f32x4 (&acc)[2][2][4][2], const Unit& u, int wr, int wc, int fr, int fq) const {
;     ...
;             for (int m = 0; m < 4; ++m) { const size_t ro = (size_t)(row0 + ai * HALF + m * 16) * 1024 + col0;
; #pragma unroll
;                 for (int bj = 0; bj < 2; ++bj)
; #pragma unroll
;                     for (int n = 0; n < 2; ++n) { const f32x4 x = *(const f32x4*)(inb + ro + bj * HALF + n * 16);
;                         *(f32x4*)(outb + ro + bj * HALF + n * 16) = x + gv[bj][n] * acc[ai][bj][m][n]; } }
	v_pk_fma_f32 v[226:227], v[76:77], v[132:133], v[226:227]
	v_pk_fma_f32 v[224:225], v[74:75], v[130:131], v[224:225]
	global_store_dwordx4 v[178:179], v[224:227], off offset:576
	global_load_dwordx4 v[212:215], v[182:183], off offset:576
	s_waitcnt vmcnt(14)
	v_pk_fma_f32 v[230:231], v[92:93], v[144:145], v[230:231]
	v_pk_fma_f32 v[228:229], v[90:91], v[142:143], v[228:229]
	global_store_dwordx4 v[180:181], v[228:231], off
	global_load_dwordx4 v[224:227], v[184:185], off
	s_waitcnt vmcnt(14)
	v_pk_fma_f32 v[234:235], v[84:85], v[140:141], v[234:235]
	v_pk_fma_f32 v[232:233], v[82:83], v[138:139], v[232:233]
	global_store_dwordx4 v[180:181], v[232:235], off offset:64
	global_load_dwordx4 v[228:231], v[184:185], off offset:64
	s_waitcnt vmcnt(14)
	v_pk_fma_f32 v[238:239], v[72:73], v[136:137], v[238:239]
	v_pk_fma_f32 v[236:237], v[70:71], v[134:135], v[236:237]
	global_store_dwordx4 v[180:181], v[236:239], off offset:512
	global_load_dwordx4 v[232:235], v[184:185], off offset:512
	s_waitcnt vmcnt(14)
	v_pk_fma_f32 v[242:243], v[68:69], v[132:133], v[242:243]
	v_pk_fma_f32 v[240:241], v[66:67], v[130:131], v[240:241]
	global_store_dwordx4 v[180:181], v[240:243], off offset:576
	global_load_dwordx4 v[236:239], v[184:185], off offset:576
	s_waitcnt vmcnt(14)
	v_pk_fma_f32 v[246:247], v[64:65], v[144:145], v[246:247]
	v_pk_fma_f32 v[244:245], v[62:63], v[142:143], v[244:245]
	global_store_dwordx4 v[182:183], v[244:247], off
	global_load_dwordx4 v[240:243], v[186:187], off
	s_waitcnt vmcnt(14)
	v_pk_fma_f32 v[250:251], v[60:61], v[140:141], v[250:251]
	v_pk_fma_f32 v[248:249], v[58:59], v[138:139], v[248:249]
	global_store_dwordx4 v[182:183], v[248:251], off offset:64
	global_load_dwordx4 v[244:247], v[186:187], off offset:64
	s_waitcnt vmcnt(14)
	v_pk_fma_f32 v[206:207], v[48:49], v[136:137], v[206:207]
	v_pk_fma_f32 v[204:205], v[46:47], v[134:135], v[204:205]
	global_store_dwordx4 v[182:183], v[204:207], off offset:512
	global_load_dwordx4 v[248:251], v[186:187], off offset:512
	s_waitcnt vmcnt(14)
	v_pk_fma_f32 v[214:215], v[44:45], v[132:133], v[214:215]
	v_pk_fma_f32 v[212:213], v[42:43], v[130:131], v[212:213]
	global_store_dwordx4 v[182:183], v[212:215], off offset:576
	global_load_dwordx4 v[204:207], v[186:187], off offset:576
	s_waitcnt vmcnt(14)
	v_pk_fma_f32 v[226:227], v[56:57], v[144:145], v[226:227]
	v_pk_fma_f32 v[224:225], v[54:55], v[142:143], v[224:225]
	global_store_dwordx4 v[184:185], v[224:227], off
	global_load_dwordx4 v[212:215], v[188:189], off
	s_waitcnt vmcnt(14)
	v_pk_fma_f32 v[230:231], v[52:53], v[140:141], v[230:231]
	v_pk_fma_f32 v[228:229], v[50:51], v[138:139], v[228:229]
	global_store_dwordx4 v[184:185], v[228:231], off offset:64
	global_load_dwordx4 v[224:227], v[188:189], off offset:64
	s_waitcnt vmcnt(14)
	v_pk_fma_f32 v[234:235], v[32:33], v[136:137], v[234:235]
	v_pk_fma_f32 v[232:233], v[30:31], v[134:135], v[232:233]
	global_store_dwordx4 v[184:185], v[232:235], off offset:512
	global_load_dwordx4 v[228:231], v[188:189], off offset:512
	s_waitcnt vmcnt(14)
	v_pk_fma_f32 v[238:239], v[28:29], v[132:133], v[238:239]
	v_pk_fma_f32 v[236:237], v[26:27], v[130:131], v[236:237]
	global_store_dwordx4 v[184:185], v[236:239], off offset:576
	global_load_dwordx4 v[232:235], v[188:189], off offset:576
	s_waitcnt vmcnt(14)
	v_pk_fma_f32 v[242:243], v[40:41], v[144:145], v[242:243]
	v_pk_fma_f32 v[240:241], v[38:39], v[142:143], v[240:241]
	global_store_dwordx4 v[186:187], v[240:243], off
	s_waitcnt vmcnt(13)
	v_pk_fma_f32 v[246:247], v[36:37], v[140:141], v[246:247]
	v_pk_fma_f32 v[244:245], v[34:35], v[138:139], v[244:245]
	global_store_dwordx4 v[186:187], v[244:247], off offset:64
	s_waitcnt vmcnt(12)
	v_pk_fma_f32 v[250:251], v[16:17], v[136:137], v[250:251]
	v_pk_fma_f32 v[248:249], v[14:15], v[134:135], v[248:249]
	global_store_dwordx4 v[186:187], v[248:251], off offset:512
	s_waitcnt vmcnt(11)
	v_pk_fma_f32 v[206:207], v[12:13], v[132:133], v[206:207]
	v_pk_fma_f32 v[204:205], v[10:11], v[130:131], v[204:205]
	global_store_dwordx4 v[186:187], v[204:207], off offset:576
	s_waitcnt vmcnt(10)
	v_pk_fma_f32 v[214:215], v[24:25], v[144:145], v[214:215]
	v_pk_fma_f32 v[212:213], v[22:23], v[142:143], v[212:213]
	global_store_dwordx4 v[188:189], v[212:215], off
	s_waitcnt vmcnt(9)
	v_pk_fma_f32 v[226:227], v[20:21], v[140:141], v[226:227]
	v_pk_fma_f32 v[224:225], v[18:19], v[138:139], v[224:225]
	global_store_dwordx4 v[188:189], v[224:227], off offset:64
	s_waitcnt vmcnt(8)
	v_pk_fma_f32 v[230:231], v[8:9], v[136:137], v[230:231]
	v_pk_fma_f32 v[228:229], v[6:7], v[134:135], v[228:229]
	global_store_dwordx4 v[188:189], v[228:231], off offset:512
	s_waitcnt vmcnt(7)
	v_pk_fma_f32 v[234:235], v[4:5], v[132:133], v[234:235]
	v_pk_fma_f32 v[232:233], v[2:3], v[130:131], v[232:233]
	global_store_dwordx4 v[188:189], v[232:235], off offset:576
	s_mov_b64 s[2:3], 0
